# outnorm fused into scan phases, scan waves at static priority 2 over the outnorm waves
# speedup vs baseline: 1.0038x; 1.0021x over previous
; DI void phase_scan_c(int wv_, int vb_, int nvb_, char* ws_, const Ctx& p, char* smem, int half) {
;     ...
;   if ((vb_ >> 1) < 64 && !(vb_ & 1)) {
;     const int blk = vb_ >> 1;
;     const int b = blk >> 3, hd = blk & 7, dv0 = wave * 32;
;     f32x16 S[4];
;     float* stp = ST + ((size_t)(blk * 4 + wave) * 64) * 64 + lane;
;     if (half == 0) {
; #pragma unroll
;       for (int mb = 0; mb < 4; ++mb) S[mb] = zero16();
;     } else {
; #pragma unroll
;       for (int mb = 0; mb < 4; ++mb)
; #pragma unroll
;         for (int i = 0; i < 16; ++i) S[mb][i] = stp[(mb * 16 + i) * 64];
;     }
;     bf16x8 gw[4], gq[4], gk[4], gqk[2];
;     ...
;     SLOAD((size_t)blk * 32)
;     __syncthreads();
;     SWRITE()
;     __syncthreads();
.Long_done:
	s_nop 0
	s_nop 0
	s_nop 0
	s_nop 0
	s_nop 0
	s_nop 0
	s_nop 0
	s_nop 0
	s_nop 0
	s_nop 0
	s_nop 0
	s_nop 0
	s_nop 0
	s_nop 0
	s_nop 0
	s_nop 0
	s_nop 0
	s_nop 0
	s_nop 0
	s_nop 0
	s_nop 0
	s_nop 0
	s_nop 0
	s_nop 0
	s_nop 0
	s_nop 0
	s_nop 0
	s_nop 0
	s_waitcnt vmcnt(0)
	s_mov_b32 s0, s33
	v_mov_b32_e32 v2, v204
.LBB0_165:
	v_readlane_b32 s2, v252, 15
	v_readlane_b32 s3, v252, 16
	s_andn2_b64 vcc, exec, s[2:3]
	s_cbranch_vccnz .LBB0_169
	s_add_u32 s4, s78, 0x10600000
	s_addc_u32 s5, s79, 0
	s_add_u32 s6, s78, 0x14600000
	s_addc_u32 s7, s79, 0
	s_add_u32 s8, s78, 0x16600000
	s_addc_u32 s9, s79, 0
	v_readlane_b32 s14, v252, 18
	s_add_u32 s10, s78, 0x18600000
	v_readlane_b32 s15, v252, 19
	s_addc_u32 s11, s79, 0
	v_lshl_or_b32 v60, s0, 6, v2
	s_lshl_b64 s[0:1], s[14:15], 1
	s_add_u32 s2, s4, s0
	s_addc_u32 s3, s5, s1
	s_add_u32 s12, s6, s0
	s_addc_u32 s13, s7, s1
	v_add_u32_e32 v62, 0x100, v60
	v_add_u32_e32 v64, 0x200, v60
	s_add_u32 s0, s8, s0
	v_ashrrev_i32_e32 v61, 31, v60
	v_ashrrev_i32_e32 v63, 31, v62
	v_ashrrev_i32_e32 v65, 31, v64
	s_addc_u32 s1, s9, s1
	v_lshlrev_b64 v[170:171], 4, v[60:61]
	v_lshlrev_b64 v[172:173], 4, v[62:63]
	v_lshlrev_b64 v[36:37], 4, v[64:65]
	v_lshl_add_u64 v[4:5], s[2:3], 0, v[170:171]
	v_lshl_add_u64 v[8:9], s[12:13], 0, v[170:171]
	v_lshl_add_u64 v[12:13], s[0:1], 0, v[170:171]
	s_waitcnt lgkmcnt(0)
	v_lshl_add_u64 v[16:17], s[2:3], 0, v[172:173]
	v_lshl_add_u64 v[20:21], s[12:13], 0, v[172:173]
	v_lshl_add_u64 v[24:25], s[0:1], 0, v[172:173]
	v_lshl_add_u64 v[28:29], s[2:3], 0, v[36:37]
	v_lshl_add_u64 v[32:33], s[12:13], 0, v[36:37]
	global_load_dwordx4 v[4:7], v[4:5], off
	s_nop 0
	global_load_dwordx4 v[8:11], v[8:9], off
	s_nop 0
	global_load_dwordx4 v[12:15], v[12:13], off
	s_nop 0
	global_load_dwordx4 v[16:19], v[16:17], off
	s_nop 0
	global_load_dwordx4 v[20:23], v[20:21], off
	s_nop 0
	global_load_dwordx4 v[24:27], v[24:25], off
	s_nop 0
	global_load_dwordx4 v[28:31], v[28:29], off
	s_nop 0
	global_load_dwordx4 v[32:35], v[32:33], off
	v_add_u32_e32 v66, 0x300, v60
	v_ashrrev_i32_e32 v67, 31, v66
	v_lshlrev_b64 v[44:45], 4, v[66:67]
	v_lshl_add_u64 v[36:37], s[0:1], 0, v[36:37]
	v_lshl_add_u64 v[48:49], s[0:1], 0, v[44:45]
	s_add_u32 s0, s10, s14
	s_addc_u32 s1, s11, s15
	v_lshl_add_u64 v[40:41], s[2:3], 0, v[44:45]
	v_lshl_add_u64 v[46:47], s[12:13], 0, v[44:45]
	v_lshl_add_u64 v[52:53], s[0:1], 0, v[170:171]
	v_lshl_add_u64 v[56:57], s[0:1], 0, v[172:173]
	global_load_dwordx4 v[36:39], v[36:37], off
	s_nop 0
	global_load_dwordx4 v[40:43], v[40:41], off
	s_nop 0
	global_load_dwordx4 v[44:47], v[46:47], off
	s_nop 0
	global_load_dwordx4 v[48:51], v[48:49], off
	s_nop 0
	global_load_dwordx4 v[52:55], v[52:53], off
	s_nop 0
	global_load_dwordx4 v[56:59], v[56:57], off
	v_lshlrev_b32_e32 v0, 4, v2
	v_and_b32_e32 v69, 0xf0, v0
	v_and_b32_e32 v70, 0x70, v0
	v_lshrrev_b32_e32 v76, 4, v60
	v_add_u32_e32 v0, v214, v69
	v_bfe_u32 v71, v2, 5, 1
	v_lshrrev_b32_e32 v77, 3, v60
	v_add_u32_e32 v70, v214, v70
	v_lshrrev_b32_e32 v69, 4, v62
	v_lshrrev_b32_e32 v78, 3, v62
	v_lshrrev_b32_e32 v79, 4, v64
	v_mad_u64_u32 v[174:175], s[0:1], v76, s19, v[0:1]
	s_movk_i32 s2, 0x90
	v_mad_u64_u32 v[176:177], s[0:1], v77, s2, v[70:71]
	v_mad_u64_u32 v[178:179], s[0:1], v69, s19, v[0:1]
	v_mad_u64_u32 v[180:181], s[0:1], v78, s2, v[70:71]
	v_mad_u64_u32 v[182:183], s[0:1], v79, s19, v[0:1]
	s_barrier
	v_and_b32_e32 v3, 31, v2
	v_ashrrev_i32_e32 v217, 6, v60
	v_lshlrev_b32_e32 v68, 5, v217
	v_ashrrev_i32_e32 v69, 31, v68
	v_lshlrev_b64 v[60:61], 3, v[60:61]
	v_lshlrev_b64 v[62:63], 3, v[62:63]
	v_lshlrev_b64 v[72:73], 3, v[64:65]
	v_lshlrev_b64 v[74:75], 3, v[66:67]
	v_readlane_b32 s44, v254, 50
	v_and_b32_e32 v216, 63, v2
	v_lshlrev_b64 v[190:191], 1, v[60:61]
	v_lshlrev_b64 v[192:193], 1, v[62:63]
	v_lshlrev_b64 v[200:201], 1, v[72:73]
	v_lshlrev_b64 v[202:203], 1, v[74:75]
	v_readlane_b32 s45, v254, 51
	s_mov_b32 s52, 0x6600000
	s_mov_b32 s56, 0x6601000
	s_mov_b32 s57, 0x6604000
	s_waitcnt vmcnt(13)
	ds_write_b128 v174, v[4:7]
	s_waitcnt vmcnt(12)
	ds_write_b128 v174, v[8:11] offset:17408
	s_waitcnt vmcnt(11)
	ds_write_b128 v176, v[12:15] offset:34816
	s_waitcnt vmcnt(10)
	ds_write_b128 v178, v[16:19]
	s_waitcnt vmcnt(9)
	ds_write_b128 v178, v[20:23] offset:17408
	s_waitcnt vmcnt(8)
	ds_write_b128 v180, v[24:27] offset:34816
	s_waitcnt vmcnt(7)
	ds_write_b128 v182, v[28:31]
	s_waitcnt vmcnt(6)
	ds_write_b128 v182, v[32:35] offset:17408
	v_lshrrev_b32_e32 v4, 3, v64
	v_mul_lo_u32 v4, v4, s2
	v_add_u32_e32 v175, v70, v4
	v_lshrrev_b32_e32 v4, 4, v66
	v_mad_u64_u32 v[184:185], s[0:1], v4, s19, v[0:1]
	v_lshrrev_b32_e32 v0, 3, v66
	v_mul_lo_u32 v0, v0, s2
	v_add_u32_e32 v177, v70, v0
	v_mul_u32_u24_e32 v0, 0x88, v3
	v_lshlrev_b32_e32 v0, 1, v0
	v_lshlrev_b32_e32 v4, 4, v71
	v_add3_u32 v179, v214, v0, v4
	v_lshlrev_b32_e32 v0, 7, v3
	v_sub_u32_e32 v181, v179, v0
	v_lshlrev_b32_e32 v0, 13, v71
	v_lshl_add_u64 v[4:5], v[68:69], 1, v[0:1]
	v_readlane_b32 s0, v253, 44
	v_lshl_or_b32 v4, v3, 1, v4
	v_readlane_b32 s1, v253, 45
	v_or_b32_e32 v68, v68, v3
	v_mov_b32_e32 v18, 0
	v_lshl_add_u64 v[186:187], s[0:1], 0, v[4:5]
	v_lshlrev_b64 v[4:5], 7, v[68:69]
	v_readlane_b32 s0, v253, 46
	v_and_or_b32 v4, v2, 32, v4
	v_readlane_b32 s1, v253, 47
	v_readlane_b32 s2, v253, 48
	s_waitcnt vmcnt(5)
	ds_write_b128 v175, v[36:39] offset:34816
	s_waitcnt vmcnt(4)
	ds_write_b128 v184, v[40:43]
	s_waitcnt vmcnt(3)
	ds_write_b128 v184, v[44:47] offset:17408
	s_waitcnt vmcnt(2)
	ds_write_b128 v177, v[48:51] offset:34816
	s_waitcnt vmcnt(1)
	ds_write_b128 v176, v[52:55] offset:53248
	s_waitcnt vmcnt(0)
; #define MFMA32(a, b, c) __builtin_amdgcn_mfma_f32_32x32x16_bf16((a), (b), (c), 0, 0, 0)
; DI void phase_scan_c(int wv_, int vb_, int nvb_, char* ws_, const Ctx& p, char* smem, int half) {
;     ...
;     if (half == 0) {
; #pragma unroll
;       for (int mb = 0; mb < 4; ++mb) S[mb] = zero16();
;     ...
;     for (int nc = 0; nc < 32; ++nc) {
;       const size_t uix = (size_t)blk * 32 + nc;
;       const float egl = GL[uix];
;       bf16x8 ucur[4];
; #pragma unroll
;       for (int tb = 0; tb < 2; ++tb) { ucur[2 * tb] = *(const bf16x8*)(CU + (uix * 128 + dv0 + c) * 64 + h * 16 + tb * 32); ucur[2 * tb + 1] = *(const bf16x8*)(CU + (uix * 128 + dv0 + c) * 64 + h * 16 + tb * 32 + 8); }
;       const u16* Wp = sW + c * 136 + h * 8;
;       const u16* Qp = sQ + c * 136 + h * 8;
;       const u16* KTp = sKT + c * 72 + h * 8;
;       const u16* QKp = sQK + c * 72 + h * 8;
;       f32x16 X[2], Oa[2];
;       X[0] = zero16(); X[1] = zero16(); Oa[0] = zero16(); Oa[1] = zero16();
; #pragma unroll
;       for (int mb = 0; mb < 4; ++mb) {
; #pragma unroll
;         for (int s = 0; s < 2; ++s) {
;           const bf16x8 sb = pack8(S[mb], s);
; #pragma unroll
;           for (int tb = 0; tb < 2; ++tb) {
;             bf16x8 a = *(const bf16x8*)(Wp + tb * 32 * 136 + mb * 32 + s * 16);
;             bf16x8 a2 = *(const bf16x8*)(Qp + tb * 32 * 136 + mb * 32 + s * 16);
;             X[tb] = MFMA32(a, sb, X[tb]);
;             Oa[tb] = MFMA32(a2, sb, Oa[tb]);
;           }
;         }
;       }
	ds_write_b128 v180, v[56:59] offset:53248
	v_lshl_add_u64 v[188:189], s[0:1], 0, v[4:5]
	s_movk_i32 s1, 0xffe0
	v_readlane_b32 s3, v253, 49
	v_mov_b32_e32 v19, v18
	v_mov_b32_e32 v20, v18
	v_mov_b32_e32 v21, v18
	v_mov_b32_e32 v22, v18
	v_mov_b32_e32 v23, v18
	v_mov_b32_e32 v24, v18
	v_mov_b32_e32 v25, v18
	v_mov_b32_e32 v26, v18
	v_mov_b32_e32 v27, v18
	v_mov_b32_e32 v28, v18
	v_mov_b32_e32 v29, v18
	v_mov_b32_e32 v30, v18
	v_mov_b32_e32 v31, v18
	v_mov_b32_e32 v32, v18
	v_mov_b32_e32 v33, v18
	v_mov_b32_e32 v50, v18
	v_mov_b32_e32 v51, v18
	v_mov_b32_e32 v52, v18
	v_mov_b32_e32 v53, v18
	v_mov_b32_e32 v54, v18
	v_mov_b32_e32 v55, v18
	v_mov_b32_e32 v56, v18
	v_mov_b32_e32 v57, v18
	v_mov_b32_e32 v58, v18
	v_mov_b32_e32 v59, v18
	v_mov_b32_e32 v60, v18
	v_mov_b32_e32 v61, v18
	v_mov_b32_e32 v62, v18
	v_mov_b32_e32 v63, v18
	v_mov_b32_e32 v64, v18
	v_mov_b32_e32 v65, v18
	v_mov_b32_e32 v34, v18
	v_mov_b32_e32 v35, v18
	v_mov_b32_e32 v36, v18
	v_mov_b32_e32 v37, v18
	v_mov_b32_e32 v38, v18
	v_mov_b32_e32 v39, v18
	v_mov_b32_e32 v40, v18
	v_mov_b32_e32 v41, v18
	v_mov_b32_e32 v42, v18
	v_mov_b32_e32 v43, v18
	v_mov_b32_e32 v44, v18
	v_mov_b32_e32 v45, v18
	v_mov_b32_e32 v46, v18
	v_mov_b32_e32 v47, v18
	v_mov_b32_e32 v48, v18
	v_mov_b32_e32 v49, v18
	v_mov_b32_e32 v2, v18
	v_mov_b32_e32 v3, v18
	v_mov_b32_e32 v4, v18
	v_mov_b32_e32 v5, v18
	v_mov_b32_e32 v6, v18
	v_mov_b32_e32 v7, v18
	v_mov_b32_e32 v8, v18
	v_mov_b32_e32 v9, v18
	v_mov_b32_e32 v10, v18
	v_mov_b32_e32 v11, v18
	v_mov_b32_e32 v12, v18
	v_mov_b32_e32 v13, v18
	v_mov_b32_e32 v14, v18
	v_mov_b32_e32 v15, v18
	v_mov_b32_e32 v16, v18
	v_mov_b32_e32 v17, v18
	s_mov_b32 s62, 0x6605000
	s_mov_b32 s63, 0x6608000
	s_mov_b32 s64, 0x6609000
	s_mov_b32 s65, 0x660c000
	s_mov_b32 s68, 0x660d000
	s_mov_b32 s69, 0x6610000
	s_mov_b32 s72, 0x6611000
	s_mov_b32 s73, 0x6614000
	s_mov_b32 s76, 0x6615000
	s_mov_b32 s77, 0x6618000
	s_mov_b32 s84, 0x6619000
	s_mov_b32 s88, 0x661c000
	s_mov_b32 s89, 0x661d000
	s_mov_b64 s[90:91], 0x20000
	s_mov_b64 s[94:95], 0x4000
	s_waitcnt lgkmcnt(0)
	s_barrier
	s_setprio 2
.LBB0_167:
	s_add_u32 s12, s2, s16
	s_addc_u32 s13, s3, s17
	v_lshl_add_u64 v[66:67], v[188:189], 0, s[16:17]
	global_load_dword v0, v1, s[12:13]
	global_load_dwordx4 v[142:145], v[66:67], off offset:-64
	global_load_dwordx4 v[138:141], v[66:67], off offset:-48
	global_load_dwordx4 v[134:137], v[66:67], off
	global_load_dwordx4 v[130:133], v[66:67], off offset:16
	ds_read_b128 v[70:73], v179 offset:17408
	ds_read_b128 v[74:77], v179
	ds_read_b128 v[146:149], v179 offset:32
	v_cvt_pk_bf16_f32 v66, v18, v19
	v_cvt_pk_bf16_f32 v67, v20, v21
	v_cvt_pk_bf16_f32 v68, v22, v23
	v_cvt_pk_bf16_f32 v69, v24, v25
	v_cvt_pk_bf16_f32 v150, v26, v27
	v_cvt_pk_bf16_f32 v151, v28, v29
	s_waitcnt lgkmcnt(1)
	v_mfma_f32_32x32x16_bf16 v[114:129], v[74:77], v[66:69], 0
	v_cvt_pk_bf16_f32 v152, v30, v31
	v_cvt_pk_bf16_f32 v153, v32, v33
	v_add_co_u32_e64 v183, s[12:13], s1, 1
	s_add_i32 s1, s1, 33
	s_and_b64 s[12:13], s[12:13], exec
	s_cselect_b32 s1, 31, s1
	v_mfma_f32_32x32x16_bf16 v[82:97], v[70:73], v[66:69], 0
	ds_read_b128 v[70:73], v179 offset:8704
	ds_read_b128 v[74:77], v179 offset:26112
	ds_read_b128 v[154:157], v179 offset:17440
	s_add_u32 s12, s44, s1
	s_addc_u32 s13, s45, 0
	s_lshl_b64 s[14:15], s[12:13], 13
	s_lshl_b64 s[12:13], s[12:13], 14
	s_add_u32 s18, s4, s12
	s_waitcnt lgkmcnt(2)
	v_mfma_f32_32x32x16_bf16 v[98:113], v[70:73], v[66:69], 0
	s_addc_u32 s19, s5, s13
	s_add_u32 s34, s6, s12
	s_addc_u32 s35, s7, s13
	s_add_u32 s12, s8, s12
	s_addc_u32 s13, s9, s13
	v_lshl_add_u64 v[158:159], s[12:13], 0, v[202:203]
	v_readfirstlane_b32 s0, v183
	s_waitcnt lgkmcnt(1)
	v_mfma_f32_32x32x16_bf16 v[66:81], v[74:77], v[66:69], 0
	v_lshl_add_u64 v[188:189], v[188:189], 0, s[94:95]
	s_mov_b32 s1, s0
	s_waitcnt vmcnt(4)
	v_mul_f32_e64 v32, v32, v0
	v_mul_f32_e64 v33, v33, v0
	v_mfma_f32_32x32x16_bf16 v[114:129], v[146:149], v[150:153], v[114:129]
	v_mul_f32_e64 v30, v30, v0
	v_mul_f32_e64 v31, v31, v0
	v_mul_f32_e64 v28, v28, v0
	v_mul_f32_e64 v29, v29, v0
	v_mul_f32_e64 v26, v26, v0
	v_mul_f32_e64 v27, v27, v0
	v_pk_mul_f32 v[24:25], v[24:25], v[0:1] op_sel_hi:[1,0]
	v_pk_mul_f32 v[22:23], v[22:23], v[0:1] op_sel_hi:[1,0]
	v_pk_mul_f32 v[20:21], v[20:21], v[0:1] op_sel_hi:[1,0]
	v_pk_mul_f32 v[18:19], v[18:19], v[0:1] op_sel_hi:[1,0]
	s_waitcnt lgkmcnt(0)
	v_mfma_f32_32x32x16_bf16 v[82:97], v[154:157], v[150:153], v[82:97]
	ds_read_b128 v[146:149], v179 offset:8736
	ds_read_b128 v[154:157], v179 offset:26144
	s_waitcnt lgkmcnt(1)
	v_mfma_f32_32x32x16_bf16 v[98:113], v[146:149], v[150:153], v[98:113]
	v_cvt_pk_bf16_f32 v146, v50, v51
	v_cvt_pk_bf16_f32 v147, v52, v53
	v_cvt_pk_bf16_f32 v148, v54, v55
	v_cvt_pk_bf16_f32 v149, v56, v57
	v_mul_f32_e64 v56, v56, v0
	v_mul_f32_e64 v57, v57, v0
	v_pk_mul_f32 v[54:55], v[54:55], v[0:1] op_sel_hi:[1,0]
	v_pk_mul_f32 v[52:53], v[52:53], v[0:1] op_sel_hi:[1,0]
	s_waitcnt lgkmcnt(0)
	v_mfma_f32_32x32x16_bf16 v[66:81], v[154:157], v[150:153], v[66:81]
	ds_read_b128 v[150:153], v179 offset:64
	ds_read_b128 v[154:157], v179 offset:17472
	v_mul_f32_e64 v50, v50, v0
	v_mul_f32_e64 v51, v51, v0
	s_waitcnt lgkmcnt(1)
	v_mfma_f32_32x32x16_bf16 v[114:129], v[150:153], v[146:149], v[114:129]
	s_waitcnt lgkmcnt(0)
	v_mfma_f32_32x32x16_bf16 v[82:97], v[154:157], v[146:149], v[82:97]
	ds_read_b128 v[150:153], v179 offset:8768
	ds_read_b128 v[154:157], v179 offset:26176
	s_waitcnt lgkmcnt(1)
	v_mfma_f32_32x32x16_bf16 v[98:113], v[150:153], v[146:149], v[98:113]
	s_waitcnt lgkmcnt(0)
; #define MFMA32(a, b, c) __builtin_amdgcn_mfma_f32_32x32x16_bf16((a), (b), (c), 0, 0, 0)
; DI float bfs(short v) { return __uint_as_float(((unsigned)(u16)v) << 16); }
; DI void phase_scan_c(int wv_, int vb_, int nvb_, char* ws_, const Ctx& p, char* smem, int half) {
;     ...
; #pragma unroll
;       for (int mb = 0; mb < 4; ++mb) {
; #pragma unroll
;         for (int s = 0; s < 2; ++s) {
;           const bf16x8 sb = pack8(S[mb], s);
; #pragma unroll
;           for (int tb = 0; tb < 2; ++tb) {
;             bf16x8 a = *(const bf16x8*)(Wp + tb * 32 * 136 + mb * 32 + s * 16);
;             bf16x8 a2 = *(const bf16x8*)(Qp + tb * 32 * 136 + mb * 32 + s * 16);
;             X[tb] = MFMA32(a, sb, X[tb]);
;             Oa[tb] = MFMA32(a2, sb, Oa[tb]);
;           }
;         }
;       }
;       bf16x8 vb[2][2];
; #pragma unroll
;       for (int tb = 0; tb < 2; ++tb) {
; #pragma unroll
;         for (int i = 0; i < 8; ++i) { X[tb][i] = bfs(ucur[2 * tb][i]) - X[tb][i]; X[tb][8 + i] = bfs(ucur[2 * tb + 1][i]) - X[tb][8 + i]; }
;         vb[tb][0] = pack8(X[tb], 0); vb[tb][1] = pack8(X[tb], 1);
	v_mfma_f32_32x32x16_bf16 v[66:81], v[154:157], v[146:149], v[66:81]
	ds_read_b128 v[150:153], v179 offset:96
	ds_read_b128 v[154:157], v179 offset:17504
	v_cvt_pk_bf16_f32 v146, v58, v59
	v_cvt_pk_bf16_f32 v147, v60, v61
	v_cvt_pk_bf16_f32 v148, v62, v63
	v_cvt_pk_bf16_f32 v149, v64, v65
	v_pk_mul_f32 v[64:65], v[64:65], v[0:1] op_sel_hi:[1,0]
	v_pk_mul_f32 v[62:63], v[62:63], v[0:1] op_sel_hi:[1,0]
	s_waitcnt lgkmcnt(1)
	v_mfma_f32_32x32x16_bf16 v[114:129], v[150:153], v[146:149], v[114:129]
	v_mul_f32_e64 v60, v60, v0
	v_mul_f32_e64 v61, v61, v0
	v_mul_f32_e64 v58, v58, v0
	v_mul_f32_e64 v59, v59, v0
	s_waitcnt lgkmcnt(0)
	v_mfma_f32_32x32x16_bf16 v[82:97], v[154:157], v[146:149], v[82:97]
	ds_read_b128 v[150:153], v179 offset:8800
	ds_read_b128 v[154:157], v179 offset:26208
	s_waitcnt lgkmcnt(1)
	v_mfma_f32_32x32x16_bf16 v[98:113], v[150:153], v[146:149], v[98:113]
	s_waitcnt lgkmcnt(0)
	v_mfma_f32_32x32x16_bf16 v[66:81], v[154:157], v[146:149], v[66:81]
	ds_read_b128 v[150:153], v179 offset:128
	ds_read_b128 v[154:157], v179 offset:17536
	v_cvt_pk_bf16_f32 v146, v34, v35
	v_cvt_pk_bf16_f32 v147, v36, v37
	v_cvt_pk_bf16_f32 v148, v38, v39
	v_cvt_pk_bf16_f32 v149, v40, v41
	v_pk_mul_f32 v[40:41], v[40:41], v[0:1] op_sel_hi:[1,0]
	v_pk_mul_f32 v[38:39], v[38:39], v[0:1] op_sel_hi:[1,0]
	s_waitcnt lgkmcnt(1)
	v_mfma_f32_32x32x16_bf16 v[114:129], v[150:153], v[146:149], v[114:129]
	v_mul_f32_e64 v36, v36, v0
	v_mul_f32_e64 v37, v37, v0
	v_mul_f32_e64 v34, v34, v0
	v_mul_f32_e64 v35, v35, v0
	s_waitcnt lgkmcnt(0)
	v_mfma_f32_32x32x16_bf16 v[82:97], v[154:157], v[146:149], v[82:97]
	ds_read_b128 v[150:153], v179 offset:8832
	ds_read_b128 v[154:157], v179 offset:26240
	s_waitcnt lgkmcnt(1)
	v_mfma_f32_32x32x16_bf16 v[98:113], v[150:153], v[146:149], v[98:113]
	s_waitcnt lgkmcnt(0)
	v_mfma_f32_32x32x16_bf16 v[66:81], v[154:157], v[146:149], v[66:81]
	ds_read_b128 v[150:153], v179 offset:160
	ds_read_b128 v[154:157], v179 offset:17568
	v_cvt_pk_bf16_f32 v146, v42, v43
	v_cvt_pk_bf16_f32 v147, v44, v45
	v_cvt_pk_bf16_f32 v148, v46, v47
	v_cvt_pk_bf16_f32 v149, v48, v49
	v_pk_mul_f32 v[48:49], v[48:49], v[0:1] op_sel_hi:[1,0]
	v_pk_mul_f32 v[46:47], v[46:47], v[0:1] op_sel_hi:[1,0]
	s_waitcnt lgkmcnt(1)
	v_mfma_f32_32x32x16_bf16 v[114:129], v[150:153], v[146:149], v[114:129]
	v_mul_f32_e64 v44, v44, v0
	v_mul_f32_e64 v45, v45, v0
	v_mul_f32_e64 v42, v42, v0
	v_mul_f32_e64 v43, v43, v0
	s_waitcnt lgkmcnt(0)
	v_mfma_f32_32x32x16_bf16 v[82:97], v[154:157], v[146:149], v[82:97]
	ds_read_b128 v[150:153], v179 offset:8864
	ds_read_b128 v[154:157], v179 offset:26272
	s_waitcnt lgkmcnt(1)
	v_mfma_f32_32x32x16_bf16 v[98:113], v[150:153], v[146:149], v[98:113]
	s_waitcnt lgkmcnt(0)
	v_mfma_f32_32x32x16_bf16 v[66:81], v[154:157], v[146:149], v[66:81]
	ds_read_b128 v[150:153], v179 offset:192
	ds_read_b128 v[154:157], v179 offset:17600
	v_cvt_pk_bf16_f32 v146, v2, v3
	v_cvt_pk_bf16_f32 v147, v4, v5
	v_cvt_pk_bf16_f32 v148, v6, v7
	v_cvt_pk_bf16_f32 v149, v8, v9
	v_pk_mul_f32 v[8:9], v[8:9], v[0:1] op_sel_hi:[1,0]
	v_pk_mul_f32 v[6:7], v[6:7], v[0:1] op_sel_hi:[1,0]
	s_waitcnt lgkmcnt(1)
	v_mfma_f32_32x32x16_bf16 v[114:129], v[150:153], v[146:149], v[114:129]
	v_mul_f32_e64 v4, v4, v0
	v_mul_f32_e64 v5, v5, v0
	v_mul_f32_e64 v2, v2, v0
	v_mul_f32_e64 v3, v3, v0
	s_waitcnt lgkmcnt(0)
	v_mfma_f32_32x32x16_bf16 v[82:97], v[154:157], v[146:149], v[82:97]
	ds_read_b128 v[150:153], v179 offset:8896
	ds_read_b128 v[154:157], v179 offset:26304
	s_waitcnt lgkmcnt(1)
	v_mfma_f32_32x32x16_bf16 v[98:113], v[150:153], v[146:149], v[98:113]
	s_waitcnt lgkmcnt(0)
	v_mfma_f32_32x32x16_bf16 v[66:81], v[154:157], v[146:149], v[66:81]
	ds_read_b128 v[150:153], v179 offset:224
	ds_read_b128 v[154:157], v179 offset:17632
	v_cvt_pk_bf16_f32 v146, v10, v11
	v_cvt_pk_bf16_f32 v147, v12, v13
	v_cvt_pk_bf16_f32 v148, v14, v15
	v_cvt_pk_bf16_f32 v149, v16, v17
	v_pk_mul_f32 v[16:17], v[16:17], v[0:1] op_sel_hi:[1,0]
	v_pk_mul_f32 v[14:15], v[14:15], v[0:1] op_sel_hi:[1,0]
	s_waitcnt lgkmcnt(1)
	v_mfma_f32_32x32x16_bf16 v[114:129], v[150:153], v[146:149], v[114:129]
	v_mul_f32_e64 v12, v12, v0
	v_mul_f32_e64 v13, v13, v0
	v_mul_f32_e64 v10, v10, v0
	v_mul_f32_e64 v11, v11, v0
	s_waitcnt lgkmcnt(0)
	v_mfma_f32_32x32x16_bf16 v[82:97], v[154:157], v[146:149], v[82:97]
	ds_read_b128 v[150:153], v179 offset:8928
	ds_read_b128 v[154:157], v179 offset:26336
	ds_read_b128 v[218:221], v181 offset:53248
	global_load_dwordx4 v[158:161], v[158:159], off
	s_waitcnt lgkmcnt(2)
	v_mfma_f32_32x32x16_bf16 v[98:113], v[150:153], v[146:149], v[98:113]
	v_lshl_add_u64 v[150:151], s[18:19], 0, v[202:203]
	global_load_dwordx4 v[150:153], v[150:151], off
	s_waitcnt lgkmcnt(1)
	v_mfma_f32_32x32x16_bf16 v[66:81], v[154:157], v[146:149], v[66:81]
	s_waitcnt vmcnt(5)
	v_and_b32_e32 v147, 0xffff0000, v142
	v_lshlrev_b32_e32 v146, 16, v142
	v_add_f32_e64 v114, v146, -v114
	v_add_f32_e64 v115, v147, -v115
	s_waitcnt vmcnt(4)
	v_and_b32_e32 v147, 0xffff0000, v138
	v_lshlrev_b32_e32 v146, 16, v138
	v_pk_add_f32 v[122:123], v[146:147], v[122:123] neg_lo:[0,1] neg_hi:[0,1]
	v_and_b32_e32 v147, 0xffff0000, v143
	v_lshlrev_b32_e32 v146, 16, v143
	v_and_b32_e32 v143, 0xffff0000, v139
	v_lshlrev_b32_e32 v142, 16, v139
	v_and_b32_e32 v139, 0xffff0000, v144
	v_lshlrev_b32_e32 v138, 16, v144
	v_pk_add_f32 v[138:139], v[138:139], v[118:119] neg_lo:[0,1] neg_hi:[0,1]
	v_and_b32_e32 v119, 0xffff0000, v140
	v_lshlrev_b32_e32 v118, 16, v140
	v_pk_add_f32 v[126:127], v[118:119], v[126:127] neg_lo:[0,1] neg_hi:[0,1]
	v_and_b32_e32 v119, 0xffff0000, v145
	v_lshlrev_b32_e32 v118, 16, v145
	v_pk_add_f32 v[116:117], v[146:147], v[116:117] neg_lo:[0,1] neg_hi:[0,1]
	v_pk_add_f32 v[124:125], v[142:143], v[124:125] neg_lo:[0,1] neg_hi:[0,1]
	v_pk_add_f32 v[142:143], v[118:119], v[120:121] neg_lo:[0,1] neg_hi:[0,1]
	v_and_b32_e32 v119, 0xffff0000, v141
	v_lshlrev_b32_e32 v118, 16, v141
	v_pk_add_f32 v[128:129], v[118:119], v[128:129] neg_lo:[0,1] neg_hi:[0,1]
	v_cvt_pk_bf16_f32 v118, v114, v115
	v_cvt_pk_bf16_f32 v119, v116, v117
	v_cvt_pk_bf16_f32 v120, v138, v139
	v_cvt_pk_bf16_f32 v121, v142, v143
	v_cvt_pk_bf16_f32 v114, v122, v123
	v_cvt_pk_bf16_f32 v115, v124, v125
	s_waitcnt lgkmcnt(0)
; #define MFMA32(a, b, c) __builtin_amdgcn_mfma_f32_32x32x16_bf16((a), (b), (c), 0, 0, 0)
; DI float bfs(short v) { return __uint_as_float(((unsigned)(u16)v) << 16); }
; DI void phase_scan_c(int wv_, int vb_, int nvb_, char* ws_, const Ctx& p, char* smem, int half) {
;     ...
;         for (int i = 0; i < 8; ++i) { X[tb][i] = bfs(ucur[2 * tb][i]) - X[tb][i]; X[tb][8 + i] = bfs(ucur[2 * tb + 1][i]) - X[tb][8 + i]; }
;         vb[tb][0] = pack8(X[tb], 0); vb[tb][1] = pack8(X[tb], 1);
;       }
;       { const int ncn = nc < 31 ? nc + 1 : 31; SLOAD((size_t)blk * 32 + ncn) }
; #pragma unroll
;       for (int tb = 0; tb < 2; ++tb)
; #pragma unroll
;         for (int tb2 = 0; tb2 < 2; ++tb2)
; #pragma unroll
;           for (int s = 0; s < 2; ++s) {
;             bf16x8 a = *(const bf16x8*)(QKp + tb * 32 * 72 + tb2 * 32 + s * 16);
;             Oa[tb] = MFMA32(a, vb[tb2][s], Oa[tb]);
;           }
; #pragma unroll
;       for (int mb = 0; mb < 4; ++mb) {
; #pragma unroll
;         for (int i = 0; i < 16; ++i) S[mb][i] *= egl;
; #pragma unroll
;         for (int tb = 0; tb < 2; ++tb)
; #pragma unroll
;           for (int s = 0; s < 2; ++s) {
;             bf16x8 a = *(const bf16x8*)(KTp + mb * 32 * 72 + tb * 32 + s * 16);
;             S[mb] = MFMA32(a, vb[tb][s], S[mb]);
;           }
;       }
	v_mfma_f32_32x32x16_bf16 v[82:97], v[218:221], v[118:121], v[82:97]
	ds_read_b128 v[218:221], v181 offset:53280
	v_cvt_pk_bf16_f32 v116, v126, v127
	v_cvt_pk_bf16_f32 v117, v128, v129
	s_waitcnt vmcnt(3)
	v_and_b32_e32 v123, 0xffff0000, v134
	v_lshlrev_b32_e32 v122, 16, v134
	v_pk_add_f32 v[98:99], v[122:123], v[98:99] neg_lo:[0,1] neg_hi:[0,1]
	s_waitcnt vmcnt(2)
	v_and_b32_e32 v123, 0xffff0000, v130
	s_waitcnt lgkmcnt(0)
	v_mfma_f32_32x32x16_bf16 v[82:97], v[218:221], v[114:117], v[82:97]
	ds_read_b128 v[218:221], v181 offset:53312
	v_lshlrev_b32_e32 v122, 16, v130
	v_add_f32_e64 v106, v122, -v106
	v_add_f32_e64 v107, v123, -v107
	v_and_b32_e32 v123, 0xffff0000, v135
	v_lshlrev_b32_e32 v122, 16, v135
	v_pk_add_f32 v[100:101], v[122:123], v[100:101] neg_lo:[0,1] neg_hi:[0,1]
	v_and_b32_e32 v123, 0xffff0000, v131
	v_lshlrev_b32_e32 v122, 16, v131
	v_pk_add_f32 v[108:109], v[122:123], v[108:109] neg_lo:[0,1] neg_hi:[0,1]
	v_and_b32_e32 v123, 0xffff0000, v136
	v_lshlrev_b32_e32 v122, 16, v136
	v_pk_add_f32 v[122:123], v[122:123], v[102:103] neg_lo:[0,1] neg_hi:[0,1]
	v_and_b32_e32 v103, 0xffff0000, v132
	v_lshlrev_b32_e32 v102, 16, v132
	v_pk_add_f32 v[110:111], v[102:103], v[110:111] neg_lo:[0,1] neg_hi:[0,1]
	v_and_b32_e32 v103, 0xffff0000, v137
	v_lshlrev_b32_e32 v102, 16, v137
	v_pk_add_f32 v[124:125], v[102:103], v[104:105] neg_lo:[0,1] neg_hi:[0,1]
	v_and_b32_e32 v103, 0xffff0000, v133
	v_lshlrev_b32_e32 v102, 16, v133
	v_pk_add_f32 v[112:113], v[102:103], v[112:113] neg_lo:[0,1] neg_hi:[0,1]
	v_cvt_pk_bf16_f32 v102, v98, v99
	v_cvt_pk_bf16_f32 v103, v100, v101
	v_cvt_pk_bf16_f32 v104, v122, v123
	v_cvt_pk_bf16_f32 v105, v124, v125
	v_cvt_pk_bf16_f32 v98, v106, v107
	v_cvt_pk_bf16_f32 v99, v108, v109
	s_waitcnt lgkmcnt(0)
	v_mfma_f32_32x32x16_bf16 v[82:97], v[218:221], v[102:105], v[82:97]
	ds_read_b128 v[218:221], v181 offset:53344
	v_cvt_pk_bf16_f32 v100, v110, v111
	v_cvt_pk_bf16_f32 v101, v112, v113
	v_lshl_add_u64 v[122:123], s[12:13], 0, v[190:191]
	v_lshl_add_u64 v[134:135], s[12:13], 0, v[192:193]
	v_lshl_add_u64 v[146:147], s[12:13], 0, v[200:201]
	s_add_u32 s12, s10, s14
	s_waitcnt lgkmcnt(0)
	v_mfma_f32_32x32x16_bf16 v[82:97], v[218:221], v[98:101], v[82:97]
	ds_read_b128 v[218:221], v181 offset:57856
	s_addc_u32 s13, s11, s15
	v_lshl_add_u64 v[106:107], s[18:19], 0, v[190:191]
	v_lshl_add_u64 v[110:111], s[34:35], 0, v[190:191]
	v_lshl_add_u64 v[126:127], s[18:19], 0, v[192:193]
	v_lshl_add_u64 v[130:131], s[34:35], 0, v[192:193]
	v_lshl_add_u64 v[138:139], s[18:19], 0, v[200:201]
	s_waitcnt lgkmcnt(0)
	v_mfma_f32_32x32x16_bf16 v[66:81], v[218:221], v[118:121], v[66:81]
	ds_read_b128 v[218:221], v181 offset:57888
	v_lshl_add_u64 v[142:143], s[34:35], 0, v[200:201]
	v_lshl_add_u64 v[154:155], s[34:35], 0, v[202:203]
	v_lshl_add_u64 v[162:163], s[12:13], 0, v[170:171]
	v_lshl_add_u64 v[166:167], s[12:13], 0, v[172:173]
	global_load_dwordx4 v[106:109], v[106:107], off
	v_cvt_pk_bf16_f32 v0, v82, s0
	s_waitcnt lgkmcnt(0)
	v_mfma_f32_32x32x16_bf16 v[66:81], v[218:221], v[114:117], v[66:81]
	ds_read_b128 v[218:221], v181 offset:57920
	global_load_dwordx4 v[110:113], v[110:111], off
	s_add_u32 s2, s2, 4
	global_load_dwordx4 v[122:125], v[122:123], off
	s_addc_u32 s3, s3, 0
	global_load_dwordx4 v[126:129], v[126:127], off
	s_waitcnt lgkmcnt(0)
	v_mfma_f32_32x32x16_bf16 v[66:81], v[218:221], v[102:105], v[66:81]
	ds_read_b128 v[218:221], v181 offset:57952
	global_load_dwordx4 v[130:133], v[130:131], off
	s_nop 0
	global_load_dwordx4 v[134:137], v[134:135], off
	s_nop 0
	global_load_dwordx4 v[138:141], v[138:139], off
	s_nop 0
	global_load_dwordx4 v[142:145], v[142:143], off
	s_waitcnt lgkmcnt(0)
	v_mfma_f32_32x32x16_bf16 v[66:81], v[218:221], v[98:101], v[66:81]
	global_load_dwordx4 v[146:149], v[146:147], off
	s_nop 0
	global_load_dwordx4 v[154:157], v[154:155], off
	s_nop 0
	global_load_dwordx4 v[162:165], v[162:163], off
	s_nop 0
	global_load_dwordx4 v[166:169], v[166:167], off
	ds_read_b128 v[218:221], v181 offset:34816
	ds_read_b128 v[222:225], v181 offset:34848
	s_waitcnt lgkmcnt(1)
	v_mfma_f32_32x32x16_bf16 v[18:33], v[218:221], v[118:121], v[18:33]
	ds_read_b128 v[218:221], v181 offset:34880
	s_waitcnt lgkmcnt(1)
	v_mfma_f32_32x32x16_bf16 v[18:33], v[222:225], v[114:117], v[18:33]
	s_waitcnt lgkmcnt(0)
	v_mfma_f32_32x32x16_bf16 v[18:33], v[218:221], v[102:105], v[18:33]
	ds_read_b128 v[218:221], v181 offset:34912
	s_waitcnt lgkmcnt(0)
	v_mfma_f32_32x32x16_bf16 v[18:33], v[218:221], v[98:101], v[18:33]
	ds_read_b128 v[218:221], v181 offset:39424
	s_waitcnt lgkmcnt(0)
	v_mfma_f32_32x32x16_bf16 v[50:65], v[218:221], v[118:121], v[50:65]
	ds_read_b128 v[218:221], v181 offset:39456
	s_waitcnt lgkmcnt(0)
	v_mfma_f32_32x32x16_bf16 v[50:65], v[218:221], v[114:117], v[50:65]
	ds_read_b128 v[218:221], v181 offset:39488
	s_waitcnt lgkmcnt(0)
	v_mfma_f32_32x32x16_bf16 v[50:65], v[218:221], v[102:105], v[50:65]
	ds_read_b128 v[218:221], v181 offset:39520
	s_waitcnt lgkmcnt(0)
	v_mfma_f32_32x32x16_bf16 v[50:65], v[218:221], v[98:101], v[50:65]
	ds_read_b128 v[218:221], v181 offset:44032
	s_waitcnt lgkmcnt(0)
	v_mfma_f32_32x32x16_bf16 v[34:49], v[218:221], v[118:121], v[34:49]
	ds_read_b128 v[218:221], v181 offset:44064
	s_waitcnt lgkmcnt(0)
	v_mfma_f32_32x32x16_bf16 v[34:49], v[218:221], v[114:117], v[34:49]
	ds_read_b128 v[218:221], v181 offset:44096
	s_waitcnt lgkmcnt(0)
	v_mfma_f32_32x32x16_bf16 v[34:49], v[218:221], v[102:105], v[34:49]
	ds_read_b128 v[218:221], v181 offset:44128
	s_waitcnt lgkmcnt(0)
	v_mfma_f32_32x32x16_bf16 v[34:49], v[218:221], v[98:101], v[34:49]
	ds_read_b128 v[218:221], v181 offset:48640
	s_waitcnt lgkmcnt(0)
; #define MFMA32(a, b, c) __builtin_amdgcn_mfma_f32_32x32x16_bf16((a), (b), (c), 0, 0, 0)
; DI u16 f2bf(float x) { return (u16)(pk2bf(x, 0.f) & 0xffffu); }
; DI int crow(int i, int h) { return (i & 3) + 8 * (i >> 2) + 4 * h; }
; DI void phase_scan_c(int wv_, int vb_, int nvb_, char* ws_, const Ctx& p, char* smem, int half) {
;     ...
;             S[mb] = MFMA32(a, vb[tb][s], S[mb]);
;           }
;       }
;       u16* op = O + ((size_t)b * SEQ + (size_t)(half * 32 + nc) * 64) * 1024 + hd * 128 + dv0 + c;
; #pragma unroll
;       for (int tb = 0; tb < 2; ++tb)
; #pragma unroll
;         for (int i = 0; i < 16; ++i) op[(size_t)(tb * 32 + crow(i, h)) * 1024] = f2bf(Oa[tb][i]);
;       __syncthreads();
	v_mfma_f32_32x32x16_bf16 v[2:17], v[218:221], v[118:121], v[2:17]
	ds_read_b128 v[118:121], v181 offset:48672
	s_waitcnt lgkmcnt(0)
	v_mfma_f32_32x32x16_bf16 v[2:17], v[118:121], v[114:117], v[2:17]
	ds_read_b128 v[114:117], v181 offset:48704
	s_waitcnt lgkmcnt(0)
	v_mfma_f32_32x32x16_bf16 v[2:17], v[114:117], v[102:105], v[2:17]
	ds_read_b128 v[102:105], v181 offset:48736
	s_waitcnt lgkmcnt(0)
	v_mfma_f32_32x32x16_bf16 v[2:17], v[102:105], v[98:101], v[2:17]
	v_lshl_add_u64 v[98:99], v[186:187], 0, s[16:17]
	v_add_co_u32_e32 v100, vcc, s52, v98
	v_lshl_add_u64 v[186:187], v[186:187], 0, s[90:91]
	s_nop 0
	v_addc_co_u32_e32 v101, vcc, 0, v99, vcc
	v_add_co_u32_e32 v102, vcc, s56, v98
	s_nop 1
	v_addc_co_u32_e32 v103, vcc, 0, v99, vcc
	global_store_short v[102:103], v0, off offset:-4096
	v_cvt_pk_bf16_f32 v0, v83, s0
	v_add_co_u32_e32 v82, vcc, s57, v98
	global_store_short v[100:101], v0, off offset:2048
	v_cvt_pk_bf16_f32 v0, v84, s0
	v_addc_co_u32_e32 v83, vcc, 0, v99, vcc
	global_store_short v[102:103], v0, off
	v_cvt_pk_bf16_f32 v0, v85, s0
	v_add_co_u32_e32 v84, vcc, s62, v98
	global_store_short v[102:103], v0, off offset:2048
	v_cvt_pk_bf16_f32 v0, v86, s0
	v_addc_co_u32_e32 v85, vcc, 0, v99, vcc
	global_store_short v[84:85], v0, off offset:-4096
	v_cvt_pk_bf16_f32 v0, v87, s0
	global_store_short v[82:83], v0, off offset:2048
	v_cvt_pk_bf16_f32 v0, v88, s0
	v_add_co_u32_e32 v82, vcc, s63, v98
	global_store_short v[84:85], v0, off
	v_cvt_pk_bf16_f32 v0, v89, s0
	v_addc_co_u32_e32 v83, vcc, 0, v99, vcc
	global_store_short v[84:85], v0, off offset:2048
	v_add_co_u32_e32 v84, vcc, s64, v98
	v_cvt_pk_bf16_f32 v0, v90, s0
	s_nop 0
	v_addc_co_u32_e32 v85, vcc, 0, v99, vcc
	global_store_short v[84:85], v0, off offset:-4096
	v_cvt_pk_bf16_f32 v0, v91, s0
	global_store_short v[82:83], v0, off offset:2048
	v_cvt_pk_bf16_f32 v0, v92, s0
	v_add_co_u32_e32 v82, vcc, s65, v98
	global_store_short v[84:85], v0, off
	v_cvt_pk_bf16_f32 v0, v93, s0
	v_addc_co_u32_e32 v83, vcc, 0, v99, vcc
	global_store_short v[84:85], v0, off offset:2048
	v_add_co_u32_e32 v84, vcc, s68, v98
	v_cvt_pk_bf16_f32 v0, v94, s0
	s_nop 0
	v_addc_co_u32_e32 v85, vcc, 0, v99, vcc
	global_store_short v[84:85], v0, off offset:-4096
	v_cvt_pk_bf16_f32 v0, v95, s0
	global_store_short v[82:83], v0, off offset:2048
	v_cvt_pk_bf16_f32 v0, v96, s0
	v_add_co_u32_e32 v82, vcc, s69, v98
	global_store_short v[84:85], v0, off
	v_cvt_pk_bf16_f32 v0, v97, s0
	v_addc_co_u32_e32 v83, vcc, 0, v99, vcc
	global_store_short v[84:85], v0, off offset:2048
	v_add_co_u32_e32 v84, vcc, s72, v98
	v_cvt_pk_bf16_f32 v0, v66, s0
	s_nop 0
	v_addc_co_u32_e32 v85, vcc, 0, v99, vcc
	global_store_short v[84:85], v0, off offset:-4096
	v_cvt_pk_bf16_f32 v0, v67, s0
	v_add_co_u32_e32 v66, vcc, s73, v98
	global_store_short v[82:83], v0, off offset:2048
	v_cvt_pk_bf16_f32 v0, v68, s0
	v_addc_co_u32_e32 v67, vcc, 0, v99, vcc
	global_store_short v[84:85], v0, off
	v_cvt_pk_bf16_f32 v0, v69, s0
	v_add_co_u32_e32 v68, vcc, s76, v98
	global_store_short v[84:85], v0, off offset:2048
	v_cvt_pk_bf16_f32 v0, v70, s0
	v_addc_co_u32_e32 v69, vcc, 0, v99, vcc
	global_store_short v[68:69], v0, off offset:-4096
	v_cvt_pk_bf16_f32 v0, v71, s0
	global_store_short v[66:67], v0, off offset:2048
	v_cvt_pk_bf16_f32 v0, v72, s0
	v_add_co_u32_e32 v66, vcc, s77, v98
	global_store_short v[68:69], v0, off
	v_cvt_pk_bf16_f32 v0, v73, s0
	v_addc_co_u32_e32 v67, vcc, 0, v99, vcc
	global_store_short v[68:69], v0, off offset:2048
	v_add_co_u32_e32 v68, vcc, s84, v98
	v_cvt_pk_bf16_f32 v0, v74, s0
	s_nop 0
	v_addc_co_u32_e32 v69, vcc, 0, v99, vcc
	global_store_short v[68:69], v0, off offset:-4096
	v_cvt_pk_bf16_f32 v0, v75, s0
	global_store_short v[66:67], v0, off offset:2048
	v_cvt_pk_bf16_f32 v0, v76, s0
	v_add_co_u32_e32 v66, vcc, s88, v98
	global_store_short v[68:69], v0, off
	v_cvt_pk_bf16_f32 v0, v77, s0
	v_addc_co_u32_e32 v67, vcc, 0, v99, vcc
	global_store_short v[68:69], v0, off offset:2048
	v_add_co_u32_e32 v68, vcc, s89, v98
	v_cvt_pk_bf16_f32 v0, v78, s0
	s_nop 0
	v_addc_co_u32_e32 v69, vcc, 0, v99, vcc
	global_store_short v[68:69], v0, off offset:-4096
	v_cvt_pk_bf16_f32 v0, v79, s0
	global_store_short v[66:67], v0, off offset:2048
	v_cvt_pk_bf16_f32 v0, v80, s0
	v_cmp_eq_u32_e32 vcc, 0, v183
	global_store_short v[68:69], v0, off
	v_cvt_pk_bf16_f32 v0, v81, s0
	s_and_b64 vcc, exec, vcc
	global_store_short v[68:69], v0, off offset:2048
	s_barrier
; DI void phase_scan_c(int wv_, int vb_, int nvb_, char* ws_, const Ctx& p, char* smem, int half) {
;     ...
;       __syncthreads();
;       SWRITE()
;       __syncthreads();
;     }
;     ...
;     if (half == 0) {
; #pragma unroll
;       for (int mb = 0; mb < 4; ++mb)
; #pragma unroll
;         for (int i = 0; i < 16; ++i) stp[(mb * 16 + i) * 64] = S[mb][i];
;     }
	s_waitcnt vmcnt(43)
	ds_write_b128 v174, v[106:109]
	s_waitcnt vmcnt(42)
	ds_write_b128 v174, v[110:113] offset:17408
	s_waitcnt vmcnt(41)
	ds_write_b128 v176, v[122:125] offset:34816
	s_waitcnt vmcnt(40)
	ds_write_b128 v178, v[126:129]
	s_waitcnt vmcnt(39)
	ds_write_b128 v178, v[130:133] offset:17408
	s_waitcnt vmcnt(38)
	ds_write_b128 v180, v[134:137] offset:34816
	s_waitcnt vmcnt(37)
	ds_write_b128 v182, v[138:141]
	s_waitcnt vmcnt(36)
	ds_write_b128 v182, v[142:145] offset:17408
	s_waitcnt vmcnt(35)
	ds_write_b128 v175, v[146:149] offset:34816
	ds_write_b128 v184, v[150:153]
	s_waitcnt vmcnt(34)
	ds_write_b128 v184, v[154:157] offset:17408
	ds_write_b128 v177, v[158:161] offset:34816
	s_waitcnt vmcnt(33)
	ds_write_b128 v176, v[162:165] offset:53248
	s_waitcnt vmcnt(32)
	ds_write_b128 v180, v[166:169] offset:53248
	s_waitcnt lgkmcnt(0)
	s_barrier
	s_cbranch_vccz .LBB0_167
	s_waitcnt vmcnt(0)
	s_barrier
	s_setprio 0
	v_readlane_b32 s0, v252, 17
	v_lshlrev_b32_e32 v0, 2, v216
	s_mov_b32 s52, 0x6600000
	v_add_u32_e32 v66, s0, v217
	v_ashrrev_i32_e32 v67, 31, v66
	v_lshlrev_b64 v[66:67], 14, v[66:67]
	v_lshl_add_u64 v[66:67], s[78:79], 0, v[66:67]
	v_lshl_add_u64 v[66:67], v[66:67], 0, v[0:1]
	s_mov_b64 s[0:1], 0x1eb00000
	v_add_co_u32_e32 v70, vcc, 0x1eb00000, v66
	v_lshl_add_u64 v[68:69], v[66:67], 0, s[0:1]
	s_nop 0
	v_addc_co_u32_e32 v71, vcc, 0, v67, vcc
	s_mov_b32 s0, 0x1eb01000
	global_store_dword v[70:71], v18, off
	global_store_dword v[68:69], v19, off offset:256
	global_store_dword v[68:69], v20, off offset:512
	global_store_dword v[68:69], v21, off offset:768
	global_store_dword v[68:69], v22, off offset:1024
	global_store_dword v[68:69], v23, off offset:1280
	global_store_dword v[68:69], v24, off offset:1536
	global_store_dword v[68:69], v25, off offset:1792
	global_store_dword v[68:69], v26, off offset:2048
	global_store_dword v[68:69], v27, off offset:2304
	global_store_dword v[68:69], v28, off offset:2560
	global_store_dword v[68:69], v29, off offset:2816
	global_store_dword v[68:69], v30, off offset:3072
	global_store_dword v[68:69], v31, off offset:3328
	global_store_dword v[68:69], v32, off offset:3584
	global_store_dword v[68:69], v33, off offset:3840
	v_add_co_u32_e32 v18, vcc, s0, v66
	s_mov_b32 s0, 0x1eb02000
	s_nop 0
	v_addc_co_u32_e32 v19, vcc, 0, v67, vcc
	v_add_co_u32_e32 v20, vcc, s0, v66
	s_mov_b32 s0, 0x1eb03000
	s_nop 0
	v_addc_co_u32_e32 v21, vcc, 0, v67, vcc
	global_store_dword v[20:21], v50, off offset:-4096
	global_store_dword v[18:19], v51, off offset:256
	global_store_dword v[18:19], v52, off offset:512
	global_store_dword v[18:19], v53, off offset:768
	global_store_dword v[18:19], v54, off offset:1024
	global_store_dword v[18:19], v55, off offset:1280
	global_store_dword v[18:19], v56, off offset:1536
	global_store_dword v[18:19], v57, off offset:1792
	global_store_dword v[18:19], v58, off offset:2048
	global_store_dword v[18:19], v59, off offset:2304
	global_store_dword v[18:19], v60, off offset:2560
	global_store_dword v[18:19], v61, off offset:2816
	global_store_dword v[18:19], v62, off offset:3072
	global_store_dword v[18:19], v63, off offset:3328
	global_store_dword v[18:19], v64, off offset:3584
	global_store_dword v[18:19], v65, off offset:3840
	global_store_dword v[20:21], v34, off
	global_store_dword v[20:21], v35, off offset:256
	global_store_dword v[20:21], v36, off offset:512
	global_store_dword v[20:21], v37, off offset:768
	global_store_dword v[20:21], v38, off offset:1024
	global_store_dword v[20:21], v39, off offset:1280
	global_store_dword v[20:21], v40, off offset:1536
	global_store_dword v[20:21], v41, off offset:1792
	global_store_dword v[20:21], v42, off offset:2048
	global_store_dword v[20:21], v43, off offset:2304
	global_store_dword v[20:21], v44, off offset:2560
	global_store_dword v[20:21], v45, off offset:2816
	global_store_dword v[20:21], v46, off offset:3072
	global_store_dword v[20:21], v47, off offset:3328
	global_store_dword v[20:21], v48, off offset:3584
	global_store_dword v[20:21], v49, off offset:3840
	v_add_co_u32_e32 v18, vcc, s0, v66
	s_nop 1
	v_addc_co_u32_e32 v19, vcc, 0, v67, vcc
	global_store_dword v[18:19], v2, off
	global_store_dword v[18:19], v3, off offset:256
	global_store_dword v[18:19], v4, off offset:512
	global_store_dword v[18:19], v5, off offset:768
	global_store_dword v[18:19], v6, off offset:1024
	global_store_dword v[18:19], v7, off offset:1280
	global_store_dword v[18:19], v8, off offset:1536
	global_store_dword v[18:19], v9, off offset:1792
	global_store_dword v[18:19], v10, off offset:2048
	global_store_dword v[18:19], v11, off offset:2304
	global_store_dword v[18:19], v12, off offset:2560
	global_store_dword v[18:19], v13, off offset:2816
	global_store_dword v[18:19], v14, off offset:3072
	global_store_dword v[18:19], v15, off offset:3328
	global_store_dword v[18:19], v16, off offset:3584
	global_store_dword v[18:19], v17, off offset:3840

; DI void phase_scan_c(int wv_, int vb_, int nvb_, char* ws_, const Ctx& p, char* smem, int half) {
;     ...
;   if ((vb_ >> 1) < 64 && (vb_ & 1)) { for (int q_ = 0; q_ < 66; ++q_) __syncthreads(); }
;   if ((vb_ >> 1) < 64 && !(vb_ & 1)) {
.Lonc_done:
	s_nop 0
	s_nop 0
	s_nop 0
	s_nop 0
	s_nop 0
	s_nop 0
	s_nop 0
	s_nop 0
	s_nop 0
	s_nop 0
	s_nop 0
	s_nop 0
	s_nop 0
	s_nop 0
	s_nop 0
	s_nop 0
	s_nop 0
	s_nop 0
	s_nop 0
	s_nop 0
	s_nop 0
	s_nop 0
	s_nop 0
	s_waitcnt vmcnt(0)
	s_mov_b32 s1, s33
	v_mov_b32_e32 v82, v204

; DI void phase_scan_c(int wv_, int vb_, int nvb_, char* ws_, const Ctx& p, char* smem, int half) {
;     ...
;   if ((vb_ >> 1) < 64 && !(vb_ & 1)) {
;     const int blk = vb_ >> 1;
;     const int b = blk >> 3, hd = blk & 7, dv0 = wave * 32;
;     f32x16 S[4];
;     float* stp = ST + ((size_t)(blk * 4 + wave) * 64) * 64 + lane;
;     if (half == 0) {
; #pragma unroll
;       for (int mb = 0; mb < 4; ++mb) S[mb] = zero16();
;     } else {
; #pragma unroll
;       for (int mb = 0; mb < 4; ++mb)
; #pragma unroll
;         for (int i = 0; i < 16; ++i) S[mb][i] = stp[(mb * 16 + i) * 64];
;     }
;     bf16x8 gw[4], gq[4], gk[4], gqk[2];
;     ...
;     SLOAD((size_t)blk * 32)
;     __syncthreads();
;     SWRITE()
;     __syncthreads();
.LBB0_231:
	s_add_u32 s6, s78, 0x10600000
	s_addc_u32 s7, s79, 0
	s_add_u32 s8, s78, 0x14600000
	s_addc_u32 s9, s79, 0
	s_add_u32 s10, s78, 0x16600000
	s_addc_u32 s11, s79, 0
	v_readlane_b32 s34, v252, 18
	s_add_u32 s14, s78, 0x18600000
	v_readlane_b32 s35, v252, 19
	s_addc_u32 s15, s79, 0
	s_lshl_b64 s[4:5], s[34:35], 1
	s_add_u32 s12, s6, s4
	s_addc_u32 s13, s7, s5
	s_add_u32 s18, s8, s4
	s_addc_u32 s19, s9, s5
	v_add_u32_e32 v130, 0x100, v80
	v_add_u32_e32 v132, 0x200, v80
	s_add_u32 s4, s10, s4
	v_ashrrev_i32_e32 v81, 31, v80
	v_ashrrev_i32_e32 v131, 31, v130
	v_ashrrev_i32_e32 v133, 31, v132
	s_addc_u32 s5, s11, s5
	v_lshlrev_b64 v[14:15], 4, v[80:81]
	v_lshlrev_b64 v[174:175], 4, v[130:131]
	v_lshlrev_b64 v[106:107], 4, v[132:133]
	v_lshl_add_u64 v[2:3], s[12:13], 0, v[14:15]
	v_lshl_add_u64 v[6:7], s[18:19], 0, v[14:15]
	v_lshl_add_u64 v[10:11], s[4:5], 0, v[14:15]
	v_lshl_add_u64 v[86:87], s[12:13], 0, v[174:175]
	v_lshl_add_u64 v[90:91], s[18:19], 0, v[174:175]
	v_lshl_add_u64 v[94:95], s[4:5], 0, v[174:175]
	v_lshl_add_u64 v[98:99], s[12:13], 0, v[106:107]
	v_lshl_add_u64 v[102:103], s[18:19], 0, v[106:107]
	global_load_dwordx4 v[2:5], v[2:3], off
	s_nop 0
	global_load_dwordx4 v[6:9], v[6:7], off
	s_nop 0
	global_load_dwordx4 v[10:13], v[10:11], off
	s_nop 0
	global_load_dwordx4 v[86:89], v[86:87], off
	s_nop 0
	global_load_dwordx4 v[90:93], v[90:91], off
	s_nop 0
	global_load_dwordx4 v[94:97], v[94:95], off
	s_nop 0
	global_load_dwordx4 v[98:101], v[98:99], off
	s_nop 0
	global_load_dwordx4 v[102:105], v[102:103], off
	v_add_u32_e32 v134, 0x300, v80
	v_ashrrev_i32_e32 v135, 31, v134
	v_lshlrev_b64 v[118:119], 4, v[134:135]
	v_lshl_add_u64 v[106:107], s[4:5], 0, v[106:107]
	v_lshl_add_u64 v[110:111], s[12:13], 0, v[118:119]
	v_lshl_add_u64 v[114:115], s[18:19], 0, v[118:119]
	v_lshl_add_u64 v[118:119], s[4:5], 0, v[118:119]
	s_add_u32 s4, s14, s34
	s_addc_u32 s5, s15, s35
	v_lshl_add_u64 v[122:123], s[4:5], 0, v[14:15]
	v_lshl_add_u64 v[126:127], s[4:5], 0, v[174:175]
	global_load_dwordx4 v[106:109], v[106:107], off
	v_lshlrev_b32_e32 v0, 4, v80
	global_load_dwordx4 v[110:113], v[110:111], off
	v_and_b32_e32 v139, 0xf0, v0
	global_load_dwordx4 v[114:117], v[114:115], off
	v_lshrrev_b32_e32 v85, 4, v80
	global_load_dwordx4 v[118:121], v[118:119], off
	v_lshrrev_b32_e32 v136, 3, v80
	global_load_dwordx4 v[122:125], v[122:123], off
	v_and_b32_e32 v140, 0x70, v0
	global_load_dwordx4 v[126:129], v[126:127], off
	s_movk_i32 s1, 0x90
	v_lshrrev_b32_e32 v142, 4, v130
	v_lshrrev_b32_e32 v143, 3, v130
	v_add_u32_e32 v0, v214, v139
	s_movk_i32 s12, 0x110
	v_mul_lo_u32 v141, v136, s1
	v_lshrrev_b32_e32 v144, 4, v132
	v_lshlrev_b64 v[136:137], 3, v[134:135]
	v_add_u32_e32 v135, v214, v140
	v_mul_lo_u32 v139, v143, s1
	v_mad_u64_u32 v[176:177], s[4:5], v85, s12, v[0:1]
	v_mad_u64_u32 v[178:179], s[4:5], v142, s12, v[0:1]
	v_add_u32_e32 v177, v135, v141
	v_add_u32_e32 v179, v135, v139
	v_mad_u64_u32 v[180:181], s[4:5], v144, s12, v[0:1]
	s_waitcnt vmcnt(63) expcnt(7) lgkmcnt(15)
	s_barrier
	v_and_b32_e32 v138, 31, v82
	v_lshrrev_b32_e32 v83, 5, v83
	s_lshl_b32 s0, s0, 16
	v_lshlrev_b32_e32 v84, 5, v84
	s_and_b32 s0, s0, 0x400000
	v_lshrrev_b32_e32 v145, 3, v132
	v_ashrrev_i32_e32 v85, 31, v84
	v_mul_lo_u32 v140, v145, s1
	v_readlane_b32 s16, v254, 62
	v_lshlrev_b64 v[80:81], 3, v[80:81]
	v_lshlrev_b64 v[130:131], 3, v[130:131]
	v_lshlrev_b64 v[132:133], 3, v[132:133]
	v_readlane_b32 s56, v254, 50
	v_readlane_b32 s17, v254, 63
	v_add_u32_e32 v181, v135, v140
	s_waitcnt vmcnt(13)
	ds_write_b128 v176, v[2:5]
	s_waitcnt vmcnt(12)
	ds_write_b128 v176, v[6:9] offset:17408
	s_waitcnt vmcnt(11)
	ds_write_b128 v177, v[10:13] offset:34816
	s_waitcnt vmcnt(10)
	ds_write_b128 v178, v[86:89]
	s_waitcnt vmcnt(9)
	ds_write_b128 v178, v[90:93] offset:17408
	s_waitcnt vmcnt(8)
	ds_write_b128 v179, v[94:97] offset:34816
	s_waitcnt vmcnt(7)
	ds_write_b128 v180, v[98:101]
	s_waitcnt vmcnt(6)
	ds_write_b128 v180, v[102:105] offset:17408
	v_lshrrev_b32_e32 v2, 4, v134
	v_mad_u64_u32 v[182:183], s[4:5], v2, s12, v[0:1]
	v_lshrrev_b32_e32 v0, 3, v134
	v_mul_lo_u32 v0, v0, s1
	v_add_u32_e32 v183, v135, v0
	v_lshlrev_b32_e32 v0, 4, v82
	v_and_b32_e32 v0, 0x70, v0
	v_add_u32_e32 v0, v214, v0
	v_add_u32_e32 v202, v0, v141
	v_add_u32_e32 v203, v0, v139
	v_mul_u32_u24_e32 v0, 0x88, v138
	v_lshlrev_b32_e32 v0, 1, v0
	v_lshlrev_b32_e32 v2, 4, v83
	v_add3_u32 v216, v214, v0, v2
	v_lshlrev_b32_e32 v0, 7, v138
	v_sub_u32_e32 v217, v216, v0
	v_lshl_or_b32 v0, v83, 13, s0
	v_lshl_add_u64 v[2:3], v[84:85], 1, v[0:1]
	v_readlane_b32 s0, v253, 44
	v_lshl_or_b32 v2, v138, 1, v2
	v_readlane_b32 s1, v253, 45
	v_or_b32_e32 v84, v84, v138
	v_readlane_b32 s4, v253, 48
	v_lshl_add_u64 v[184:185], s[0:1], 0, v[2:3]
	v_lshlrev_b64 v[2:3], 7, v[84:85]
	v_readlane_b32 s0, v253, 46
	v_and_or_b32 v2, v82, 32, v2
	v_readlane_b32 s1, v253, 47
	v_lshlrev_b64 v[188:189], 1, v[80:81]
	v_lshlrev_b64 v[190:191], 1, v[130:131]
	v_lshl_add_u64 v[186:187], s[0:1], 0, v[2:3]
	s_movk_i32 s1, 0xffe0
	v_lshlrev_b64 v[192:193], 1, v[132:133]
	v_lshlrev_b64 v[200:201], 1, v[136:137]
	v_readlane_b32 s5, v253, 49
	v_readlane_b32 s57, v254, 51
	s_mov_b32 s52, 0x6600000
	s_mov_b32 s62, 0x6601000
	s_mov_b32 s63, 0x6604000
	s_mov_b32 s64, 0x6605000
	s_mov_b32 s65, 0x6608000
	s_mov_b32 s68, 0x6609000
	s_mov_b32 s69, 0x660c000
	s_mov_b32 s72, 0x660d000
	s_mov_b32 s73, 0x6610000
	s_mov_b32 s76, 0x6611000
	s_mov_b32 s77, 0x6614000
	s_mov_b32 s88, 0x6615000
	s_mov_b32 s89, 0x6618000
	s_mov_b32 s90, 0x6619000
	s_mov_b32 s91, 0x661c000
	s_mov_b32 s94, 0x661d000
	s_mov_b64 s[96:97], 0x20000
	s_mov_b64 s[2:3], 0x4000
	s_waitcnt vmcnt(5)
	ds_write_b128 v181, v[106:109] offset:34816
	s_waitcnt vmcnt(4)
	ds_write_b128 v182, v[110:113]
	s_waitcnt vmcnt(3)
	ds_write_b128 v182, v[114:117] offset:17408
	s_waitcnt vmcnt(2)
	ds_write_b128 v183, v[118:121] offset:34816
	s_waitcnt vmcnt(1)
	ds_write_b128 v202, v[122:125] offset:53248
	s_waitcnt vmcnt(0)
	ds_write_b128 v203, v[126:129] offset:53248
	s_waitcnt lgkmcnt(0)
	s_barrier
	s_setprio 2
; #define MFMA32(a, b, c) __builtin_amdgcn_mfma_f32_32x32x16_bf16((a), (b), (c), 0, 0, 0)
; DI void phase_scan_c(int wv_, int vb_, int nvb_, char* ws_, const Ctx& p, char* smem, int half) {
;     ...
;     for (int nc = 0; nc < 32; ++nc) {
;       const size_t uix = (size_t)blk * 32 + nc;
;       const float egl = GL[uix];
;       bf16x8 ucur[4];
; #pragma unroll
;       for (int tb = 0; tb < 2; ++tb) { ucur[2 * tb] = *(const bf16x8*)(CU + (uix * 128 + dv0 + c) * 64 + h * 16 + tb * 32); ucur[2 * tb + 1] = *(const bf16x8*)(CU + (uix * 128 + dv0 + c) * 64 + h * 16 + tb * 32 + 8); }
;       const u16* Wp = sW + c * 136 + h * 8;
;       const u16* Qp = sQ + c * 136 + h * 8;
;       const u16* KTp = sKT + c * 72 + h * 8;
;       const u16* QKp = sQK + c * 72 + h * 8;
;       f32x16 X[2], Oa[2];
;       X[0] = zero16(); X[1] = zero16(); Oa[0] = zero16(); Oa[1] = zero16();
; #pragma unroll
;       for (int mb = 0; mb < 4; ++mb) {
; #pragma unroll
;         for (int s = 0; s < 2; ++s) {
;           const bf16x8 sb = pack8(S[mb], s);
; #pragma unroll
;           for (int tb = 0; tb < 2; ++tb) {
;             bf16x8 a = *(const bf16x8*)(Wp + tb * 32 * 136 + mb * 32 + s * 16);
;             bf16x8 a2 = *(const bf16x8*)(Qp + tb * 32 * 136 + mb * 32 + s * 16);
;             X[tb] = MFMA32(a, sb, X[tb]);
;             Oa[tb] = MFMA32(a2, sb, Oa[tb]);
;           }
;         }
;       }
.LBB0_232:
	s_add_u32 s12, s4, s16
	s_addc_u32 s13, s5, s17
	v_lshl_add_u64 v[2:3], v[186:187], 0, s[16:17]
	global_load_dword v0, v1, s[12:13]
	global_load_dwordx4 v[144:147], v[2:3], off offset:-64
	global_load_dwordx4 v[10:13], v[2:3], off offset:-48
	global_load_dwordx4 v[6:9], v[2:3], off
	s_nop 0
	global_load_dwordx4 v[2:5], v[2:3], off offset:16
	ds_read_b128 v[84:87], v216 offset:17408
	ds_read_b128 v[88:91], v216
	ds_read_b128 v[148:151], v216 offset:32
	v_cvt_pk_bf16_f32 v80, v16, v17
	v_cvt_pk_bf16_f32 v81, v18, v19
	v_cvt_pk_bf16_f32 v82, v20, v21
	v_cvt_pk_bf16_f32 v83, v22, v23
	v_cvt_pk_bf16_f32 v152, v24, v25
	v_cvt_pk_bf16_f32 v153, v26, v27
	s_waitcnt lgkmcnt(1)
	v_mfma_f32_32x32x16_bf16 v[128:143], v[88:91], v[80:83], 0
	v_cvt_pk_bf16_f32 v154, v28, v29
	v_cvt_pk_bf16_f32 v155, v30, v31
	v_add_co_u32_e64 v218, s[12:13], s1, 1
	s_add_i32 s1, s1, 33
	s_and_b64 s[12:13], s[12:13], exec
	s_cselect_b32 s1, 31, s1
	v_mfma_f32_32x32x16_bf16 v[96:111], v[84:87], v[80:83], 0
	ds_read_b128 v[84:87], v216 offset:8704
	ds_read_b128 v[88:91], v216 offset:26112
	ds_read_b128 v[156:159], v216 offset:17440
	s_add_u32 s12, s56, s1
	s_addc_u32 s13, s57, 0
	s_lshl_b64 s[18:19], s[12:13], 13
	s_lshl_b64 s[12:13], s[12:13], 14
	s_add_u32 s34, s6, s12
	s_waitcnt lgkmcnt(2)
	v_mfma_f32_32x32x16_bf16 v[112:127], v[84:87], v[80:83], 0
	s_addc_u32 s35, s7, s13
	s_add_u32 s44, s8, s12
	s_addc_u32 s45, s9, s13
	s_add_u32 s12, s10, s12
	s_addc_u32 s13, s11, s13
	v_lshl_add_u64 v[160:161], s[12:13], 0, v[200:201]
	v_readfirstlane_b32 s0, v218
	s_waitcnt lgkmcnt(1)
	v_mfma_f32_32x32x16_bf16 v[80:95], v[88:91], v[80:83], 0
	v_lshl_add_u64 v[186:187], v[186:187], 0, s[2:3]
	s_mov_b32 s1, s0
	s_waitcnt vmcnt(4)
	v_mul_f32_e64 v30, v30, v0
	v_mul_f32_e64 v31, v31, v0
	v_mfma_f32_32x32x16_bf16 v[128:143], v[148:151], v[152:155], v[128:143]
	v_mul_f32_e64 v28, v28, v0
	v_mul_f32_e64 v29, v29, v0
	v_mul_f32_e64 v26, v26, v0
	v_mul_f32_e64 v27, v27, v0
	v_mul_f32_e64 v24, v24, v0
	v_mul_f32_e64 v25, v25, v0
	v_pk_mul_f32 v[22:23], v[22:23], v[0:1] op_sel_hi:[1,0]
	v_pk_mul_f32 v[20:21], v[20:21], v[0:1] op_sel_hi:[1,0]
	v_pk_mul_f32 v[18:19], v[18:19], v[0:1] op_sel_hi:[1,0]
	v_pk_mul_f32 v[16:17], v[16:17], v[0:1] op_sel_hi:[1,0]
	s_waitcnt lgkmcnt(0)
	v_mfma_f32_32x32x16_bf16 v[96:111], v[156:159], v[152:155], v[96:111]
	ds_read_b128 v[148:151], v216 offset:8736
	ds_read_b128 v[156:159], v216 offset:26144
	s_waitcnt lgkmcnt(1)
	v_mfma_f32_32x32x16_bf16 v[112:127], v[148:151], v[152:155], v[112:127]
	v_cvt_pk_bf16_f32 v148, v32, v33
	v_cvt_pk_bf16_f32 v149, v34, v35
	v_cvt_pk_bf16_f32 v150, v36, v37
	v_cvt_pk_bf16_f32 v151, v38, v39
	v_mul_f32_e64 v38, v38, v0
	v_mul_f32_e64 v39, v39, v0
	v_pk_mul_f32 v[36:37], v[36:37], v[0:1] op_sel_hi:[1,0]
	v_pk_mul_f32 v[34:35], v[34:35], v[0:1] op_sel_hi:[1,0]
	s_waitcnt lgkmcnt(0)
	v_mfma_f32_32x32x16_bf16 v[80:95], v[156:159], v[152:155], v[80:95]
	ds_read_b128 v[152:155], v216 offset:64
	ds_read_b128 v[156:159], v216 offset:17472
	v_mul_f32_e64 v32, v32, v0
	v_mul_f32_e64 v33, v33, v0
	s_waitcnt lgkmcnt(1)
	v_mfma_f32_32x32x16_bf16 v[128:143], v[152:155], v[148:151], v[128:143]
	s_waitcnt lgkmcnt(0)
	v_mfma_f32_32x32x16_bf16 v[96:111], v[156:159], v[148:151], v[96:111]
	ds_read_b128 v[152:155], v216 offset:8768
	ds_read_b128 v[156:159], v216 offset:26176
	s_waitcnt lgkmcnt(1)
	v_mfma_f32_32x32x16_bf16 v[112:127], v[152:155], v[148:151], v[112:127]
	s_waitcnt lgkmcnt(0)
	v_mfma_f32_32x32x16_bf16 v[80:95], v[156:159], v[148:151], v[80:95]
	ds_read_b128 v[152:155], v216 offset:96
	ds_read_b128 v[156:159], v216 offset:17504
	v_cvt_pk_bf16_f32 v148, v40, v41
	v_cvt_pk_bf16_f32 v149, v42, v43
	v_cvt_pk_bf16_f32 v150, v44, v45
	v_cvt_pk_bf16_f32 v151, v46, v47
	v_pk_mul_f32 v[46:47], v[46:47], v[0:1] op_sel_hi:[1,0]
	v_pk_mul_f32 v[44:45], v[44:45], v[0:1] op_sel_hi:[1,0]
	s_waitcnt lgkmcnt(1)
	v_mfma_f32_32x32x16_bf16 v[128:143], v[152:155], v[148:151], v[128:143]
	v_mul_f32_e64 v42, v42, v0
	v_mul_f32_e64 v43, v43, v0
	v_mul_f32_e64 v40, v40, v0
	v_mul_f32_e64 v41, v41, v0
	s_waitcnt lgkmcnt(0)
	v_mfma_f32_32x32x16_bf16 v[96:111], v[156:159], v[148:151], v[96:111]
	ds_read_b128 v[152:155], v216 offset:8800
	ds_read_b128 v[156:159], v216 offset:26208
	s_waitcnt lgkmcnt(1)
	v_mfma_f32_32x32x16_bf16 v[112:127], v[152:155], v[148:151], v[112:127]
	s_waitcnt lgkmcnt(0)
	v_mfma_f32_32x32x16_bf16 v[80:95], v[156:159], v[148:151], v[80:95]
	ds_read_b128 v[152:155], v216 offset:128
	ds_read_b128 v[156:159], v216 offset:17536
	v_cvt_pk_bf16_f32 v148, v48, v49
	v_cvt_pk_bf16_f32 v149, v50, v51
	v_cvt_pk_bf16_f32 v150, v52, v53
	v_cvt_pk_bf16_f32 v151, v54, v55
	v_pk_mul_f32 v[54:55], v[54:55], v[0:1] op_sel_hi:[1,0]
	v_pk_mul_f32 v[52:53], v[52:53], v[0:1] op_sel_hi:[1,0]
	s_waitcnt lgkmcnt(1)
	v_mfma_f32_32x32x16_bf16 v[128:143], v[152:155], v[148:151], v[128:143]
	v_mul_f32_e64 v50, v50, v0
	v_mul_f32_e64 v51, v51, v0
	v_mul_f32_e64 v48, v48, v0
	v_mul_f32_e64 v49, v49, v0
	s_waitcnt lgkmcnt(0)
	v_mfma_f32_32x32x16_bf16 v[96:111], v[156:159], v[148:151], v[96:111]
	ds_read_b128 v[152:155], v216 offset:8832
	ds_read_b128 v[156:159], v216 offset:26240
	s_waitcnt lgkmcnt(1)
	v_mfma_f32_32x32x16_bf16 v[112:127], v[152:155], v[148:151], v[112:127]
	s_waitcnt lgkmcnt(0)
	v_mfma_f32_32x32x16_bf16 v[80:95], v[156:159], v[148:151], v[80:95]
	ds_read_b128 v[152:155], v216 offset:160
	ds_read_b128 v[156:159], v216 offset:17568
	v_cvt_pk_bf16_f32 v148, v56, v57
	v_cvt_pk_bf16_f32 v149, v58, v59
	v_cvt_pk_bf16_f32 v150, v60, v61
	v_cvt_pk_bf16_f32 v151, v62, v63
	v_pk_mul_f32 v[62:63], v[62:63], v[0:1] op_sel_hi:[1,0]
	v_pk_mul_f32 v[60:61], v[60:61], v[0:1] op_sel_hi:[1,0]
	s_waitcnt lgkmcnt(1)
; #define MFMA32(a, b, c) __builtin_amdgcn_mfma_f32_32x32x16_bf16((a), (b), (c), 0, 0, 0)
; DI float bfs(short v) { return __uint_as_float(((unsigned)(u16)v) << 16); }
; DI void phase_scan_c(int wv_, int vb_, int nvb_, char* ws_, const Ctx& p, char* smem, int half) {
;     ...
; #pragma unroll
;       for (int mb = 0; mb < 4; ++mb) {
; #pragma unroll
;         for (int s = 0; s < 2; ++s) {
;           const bf16x8 sb = pack8(S[mb], s);
; #pragma unroll
;           for (int tb = 0; tb < 2; ++tb) {
;             bf16x8 a = *(const bf16x8*)(Wp + tb * 32 * 136 + mb * 32 + s * 16);
;             bf16x8 a2 = *(const bf16x8*)(Qp + tb * 32 * 136 + mb * 32 + s * 16);
;             X[tb] = MFMA32(a, sb, X[tb]);
;             Oa[tb] = MFMA32(a2, sb, Oa[tb]);
;           }
;         }
;       }
;       bf16x8 vb[2][2];
; #pragma unroll
;       for (int tb = 0; tb < 2; ++tb) {
; #pragma unroll
;         for (int i = 0; i < 8; ++i) { X[tb][i] = bfs(ucur[2 * tb][i]) - X[tb][i]; X[tb][8 + i] = bfs(ucur[2 * tb + 1][i]) - X[tb][8 + i]; }
;         vb[tb][0] = pack8(X[tb], 0); vb[tb][1] = pack8(X[tb], 1);
	v_mfma_f32_32x32x16_bf16 v[128:143], v[152:155], v[148:151], v[128:143]
	v_mul_f32_e64 v58, v58, v0
	v_mul_f32_e64 v59, v59, v0
	v_mul_f32_e64 v56, v56, v0
	v_mul_f32_e64 v57, v57, v0
	s_waitcnt lgkmcnt(0)
	v_mfma_f32_32x32x16_bf16 v[96:111], v[156:159], v[148:151], v[96:111]
	ds_read_b128 v[152:155], v216 offset:8864
	ds_read_b128 v[156:159], v216 offset:26272
	s_waitcnt lgkmcnt(1)
	v_mfma_f32_32x32x16_bf16 v[112:127], v[152:155], v[148:151], v[112:127]
	s_waitcnt lgkmcnt(0)
	v_mfma_f32_32x32x16_bf16 v[80:95], v[156:159], v[148:151], v[80:95]
	ds_read_b128 v[152:155], v216 offset:192
	ds_read_b128 v[156:159], v216 offset:17600
	v_cvt_pk_bf16_f32 v148, v64, v65
	v_cvt_pk_bf16_f32 v149, v66, v67
	v_cvt_pk_bf16_f32 v150, v68, v69
	v_cvt_pk_bf16_f32 v151, v70, v71
	v_pk_mul_f32 v[70:71], v[70:71], v[0:1] op_sel_hi:[1,0]
	v_pk_mul_f32 v[68:69], v[68:69], v[0:1] op_sel_hi:[1,0]
	s_waitcnt lgkmcnt(1)
	v_mfma_f32_32x32x16_bf16 v[128:143], v[152:155], v[148:151], v[128:143]
	v_mul_f32_e64 v66, v66, v0
	v_mul_f32_e64 v67, v67, v0
	v_mul_f32_e64 v64, v64, v0
	v_mul_f32_e64 v65, v65, v0
	s_waitcnt lgkmcnt(0)
	v_mfma_f32_32x32x16_bf16 v[96:111], v[156:159], v[148:151], v[96:111]
	ds_read_b128 v[152:155], v216 offset:8896
	ds_read_b128 v[156:159], v216 offset:26304
	s_waitcnt lgkmcnt(1)
	v_mfma_f32_32x32x16_bf16 v[112:127], v[152:155], v[148:151], v[112:127]
	s_waitcnt lgkmcnt(0)
	v_mfma_f32_32x32x16_bf16 v[80:95], v[156:159], v[148:151], v[80:95]
	ds_read_b128 v[152:155], v216 offset:224
	ds_read_b128 v[156:159], v216 offset:17632
	v_cvt_pk_bf16_f32 v148, v72, v73
	v_cvt_pk_bf16_f32 v149, v74, v75
	v_cvt_pk_bf16_f32 v150, v76, v77
	v_cvt_pk_bf16_f32 v151, v78, v79
	v_pk_mul_f32 v[78:79], v[78:79], v[0:1] op_sel_hi:[1,0]
	v_pk_mul_f32 v[76:77], v[76:77], v[0:1] op_sel_hi:[1,0]
	s_waitcnt lgkmcnt(1)
	v_mfma_f32_32x32x16_bf16 v[128:143], v[152:155], v[148:151], v[128:143]
	v_mul_f32_e64 v74, v74, v0
	v_mul_f32_e64 v75, v75, v0
	v_mul_f32_e64 v72, v72, v0
	v_mul_f32_e64 v73, v73, v0
	s_waitcnt lgkmcnt(0)
	v_mfma_f32_32x32x16_bf16 v[96:111], v[156:159], v[148:151], v[96:111]
	ds_read_b128 v[152:155], v216 offset:8928
	ds_read_b128 v[156:159], v216 offset:26336
	ds_read_b128 v[220:223], v217 offset:53248
	global_load_dwordx4 v[160:163], v[160:161], off
	s_waitcnt lgkmcnt(2)
	v_mfma_f32_32x32x16_bf16 v[112:127], v[152:155], v[148:151], v[112:127]
	v_lshl_add_u64 v[152:153], s[34:35], 0, v[200:201]
	global_load_dwordx4 v[152:155], v[152:153], off
	s_waitcnt lgkmcnt(1)
	v_mfma_f32_32x32x16_bf16 v[80:95], v[156:159], v[148:151], v[80:95]
	s_waitcnt vmcnt(5)
	v_and_b32_e32 v149, 0xffff0000, v144
	v_lshlrev_b32_e32 v148, 16, v144
	v_add_f32_e64 v128, v148, -v128
	v_add_f32_e64 v129, v149, -v129
	s_waitcnt vmcnt(4)
	v_and_b32_e32 v149, 0xffff0000, v10
	v_lshlrev_b32_e32 v148, 16, v10
	v_pk_add_f32 v[136:137], v[148:149], v[136:137] neg_lo:[0,1] neg_hi:[0,1]
	v_and_b32_e32 v149, 0xffff0000, v145
	v_lshlrev_b32_e32 v148, 16, v145
	v_and_b32_e32 v145, 0xffff0000, v11
	v_lshlrev_b32_e32 v144, 16, v11
	v_and_b32_e32 v11, 0xffff0000, v146
	v_lshlrev_b32_e32 v10, 16, v146
	v_pk_add_f32 v[10:11], v[10:11], v[132:133] neg_lo:[0,1] neg_hi:[0,1]
	v_and_b32_e32 v133, 0xffff0000, v12
	v_lshlrev_b32_e32 v132, 16, v12
	v_pk_add_f32 v[132:133], v[132:133], v[140:141] neg_lo:[0,1] neg_hi:[0,1]
	v_and_b32_e32 v141, 0xffff0000, v147
	v_lshlrev_b32_e32 v140, 16, v147
	v_pk_add_f32 v[130:131], v[148:149], v[130:131] neg_lo:[0,1] neg_hi:[0,1]
	v_pk_add_f32 v[134:135], v[140:141], v[134:135] neg_lo:[0,1] neg_hi:[0,1]
	v_cvt_pk_bf16_f32 v128, v128, v129
	v_cvt_pk_bf16_f32 v129, v130, v131
	v_cvt_pk_bf16_f32 v130, v10, v11
	v_cvt_pk_bf16_f32 v131, v134, v135
	v_and_b32_e32 v141, 0xffff0000, v13
	v_lshlrev_b32_e32 v140, 16, v13
	s_waitcnt lgkmcnt(0)
	v_mfma_f32_32x32x16_bf16 v[96:111], v[220:223], v[128:131], v[96:111]
	ds_read_b128 v[220:223], v217 offset:53280
	v_add_f32_e64 v138, v144, -v138
	v_add_f32_e64 v139, v145, -v139
	v_add_f32_e64 v140, v140, -v142
	v_add_f32_e64 v141, v141, -v143
	v_cvt_pk_bf16_f32 v10, v136, v137
	v_cvt_pk_bf16_f32 v11, v138, v139
	v_cvt_pk_bf16_f32 v12, v132, v133
	v_cvt_pk_bf16_f32 v13, v140, v141
	s_waitcnt vmcnt(3)
	v_and_b32_e32 v133, 0xffff0000, v6
	v_lshlrev_b32_e32 v132, 16, v6
	s_waitcnt lgkmcnt(0)
	v_mfma_f32_32x32x16_bf16 v[96:111], v[220:223], v[10:13], v[96:111]
	ds_read_b128 v[220:223], v217 offset:53312
	v_add_f32_e64 v112, v132, -v112
	v_add_f32_e64 v113, v133, -v113
	s_waitcnt vmcnt(2)
	v_and_b32_e32 v133, 0xffff0000, v2
	v_lshlrev_b32_e32 v132, 16, v2
	v_pk_add_f32 v[120:121], v[132:133], v[120:121] neg_lo:[0,1] neg_hi:[0,1]
	v_and_b32_e32 v133, 0xffff0000, v7
	v_lshlrev_b32_e32 v132, 16, v7
	v_and_b32_e32 v7, 0xffff0000, v3
	v_lshlrev_b32_e32 v6, 16, v3
	v_pk_add_f32 v[122:123], v[6:7], v[122:123] neg_lo:[0,1] neg_hi:[0,1]
	v_and_b32_e32 v3, 0xffff0000, v8
	v_lshlrev_b32_e32 v2, 16, v8
	v_and_b32_e32 v7, 0xffff0000, v4
	v_lshlrev_b32_e32 v6, 16, v4
	v_pk_add_f32 v[2:3], v[2:3], v[116:117] neg_lo:[0,1] neg_hi:[0,1]
	v_pk_add_f32 v[116:117], v[6:7], v[124:125] neg_lo:[0,1] neg_hi:[0,1]
	v_and_b32_e32 v7, 0xffff0000, v9
	v_lshlrev_b32_e32 v6, 16, v9
	v_pk_add_f32 v[114:115], v[132:133], v[114:115] neg_lo:[0,1] neg_hi:[0,1]
	v_pk_add_f32 v[118:119], v[6:7], v[118:119] neg_lo:[0,1] neg_hi:[0,1]
	v_and_b32_e32 v7, 0xffff0000, v5
	v_lshlrev_b32_e32 v6, 16, v5
	v_pk_add_f32 v[124:125], v[6:7], v[126:127] neg_lo:[0,1] neg_hi:[0,1]
	v_cvt_pk_bf16_f32 v6, v112, v113
	v_cvt_pk_bf16_f32 v7, v114, v115
	v_cvt_pk_bf16_f32 v8, v2, v3
	v_cvt_pk_bf16_f32 v9, v118, v119
	v_cvt_pk_bf16_f32 v2, v120, v121
	v_cvt_pk_bf16_f32 v3, v122, v123
	s_waitcnt lgkmcnt(0)
; #define MFMA32(a, b, c) __builtin_amdgcn_mfma_f32_32x32x16_bf16((a), (b), (c), 0, 0, 0)
; DI void phase_scan_c(int wv_, int vb_, int nvb_, char* ws_, const Ctx& p, char* smem, int half) {
;     ...
;       { const int ncn = nc < 31 ? nc + 1 : 31; SLOAD((size_t)blk * 32 + ncn) }
; #pragma unroll
;       for (int tb = 0; tb < 2; ++tb)
; #pragma unroll
;         for (int tb2 = 0; tb2 < 2; ++tb2)
; #pragma unroll
;           for (int s = 0; s < 2; ++s) {
;             bf16x8 a = *(const bf16x8*)(QKp + tb * 32 * 72 + tb2 * 32 + s * 16);
;             Oa[tb] = MFMA32(a, vb[tb2][s], Oa[tb]);
;           }
; #pragma unroll
;       for (int mb = 0; mb < 4; ++mb) {
; #pragma unroll
;         for (int i = 0; i < 16; ++i) S[mb][i] *= egl;
; #pragma unroll
;         for (int tb = 0; tb < 2; ++tb)
; #pragma unroll
;           for (int s = 0; s < 2; ++s) {
;             bf16x8 a = *(const bf16x8*)(KTp + mb * 32 * 72 + tb * 32 + s * 16);
;             S[mb] = MFMA32(a, vb[tb][s], S[mb]);
;           }
;       }
	v_mfma_f32_32x32x16_bf16 v[96:111], v[220:223], v[6:9], v[96:111]
	ds_read_b128 v[220:223], v217 offset:53344
	v_cvt_pk_bf16_f32 v4, v116, v117
	v_cvt_pk_bf16_f32 v5, v124, v125
	v_lshl_add_u64 v[120:121], s[12:13], 0, v[188:189]
	v_lshl_add_u64 v[136:137], s[12:13], 0, v[190:191]
	v_lshl_add_u64 v[148:149], s[12:13], 0, v[192:193]
	s_add_u32 s12, s14, s18
	s_waitcnt lgkmcnt(0)
	v_mfma_f32_32x32x16_bf16 v[96:111], v[220:223], v[2:5], v[96:111]
	ds_read_b128 v[220:223], v217 offset:57856
	s_addc_u32 s13, s15, s19
	v_lshl_add_u64 v[112:113], s[34:35], 0, v[188:189]
	v_lshl_add_u64 v[116:117], s[44:45], 0, v[188:189]
	v_lshl_add_u64 v[124:125], s[34:35], 0, v[190:191]
	v_lshl_add_u64 v[132:133], s[44:45], 0, v[190:191]
	v_lshl_add_u64 v[140:141], s[34:35], 0, v[192:193]
	s_waitcnt lgkmcnt(0)
	v_mfma_f32_32x32x16_bf16 v[80:95], v[220:223], v[128:131], v[80:95]
	ds_read_b128 v[220:223], v217 offset:57888
	v_lshl_add_u64 v[144:145], s[44:45], 0, v[192:193]
	v_lshl_add_u64 v[156:157], s[44:45], 0, v[200:201]
	v_lshl_add_u64 v[164:165], s[12:13], 0, v[14:15]
	v_lshl_add_u64 v[168:169], s[12:13], 0, v[174:175]
	global_load_dwordx4 v[112:115], v[112:113], off
	v_cvt_pk_bf16_f32 v0, v96, s0
	s_waitcnt lgkmcnt(0)
	v_mfma_f32_32x32x16_bf16 v[80:95], v[220:223], v[10:13], v[80:95]
	ds_read_b128 v[220:223], v217 offset:57920
	global_load_dwordx4 v[116:119], v[116:117], off
	s_add_u32 s4, s4, 4
	global_load_dwordx4 v[120:123], v[120:121], off
	s_addc_u32 s5, s5, 0
	global_load_dwordx4 v[124:127], v[124:125], off
	s_waitcnt lgkmcnt(0)
	v_mfma_f32_32x32x16_bf16 v[80:95], v[220:223], v[6:9], v[80:95]
	ds_read_b128 v[220:223], v217 offset:57952
	global_load_dwordx4 v[132:135], v[132:133], off
	s_nop 0
	global_load_dwordx4 v[136:139], v[136:137], off
	s_nop 0
	global_load_dwordx4 v[140:143], v[140:141], off
	s_nop 0
	global_load_dwordx4 v[144:147], v[144:145], off
	s_waitcnt lgkmcnt(0)
	v_mfma_f32_32x32x16_bf16 v[80:95], v[220:223], v[2:5], v[80:95]
	global_load_dwordx4 v[148:151], v[148:149], off
	s_nop 0
	global_load_dwordx4 v[156:159], v[156:157], off
	s_nop 0
	global_load_dwordx4 v[164:167], v[164:165], off
	s_nop 0
	global_load_dwordx4 v[168:171], v[168:169], off
	ds_read_b128 v[220:223], v217 offset:34816
	ds_read_b128 v[224:227], v217 offset:34848
	s_waitcnt lgkmcnt(1)
	v_mfma_f32_32x32x16_bf16 v[16:31], v[220:223], v[128:131], v[16:31]
	ds_read_b128 v[220:223], v217 offset:34880
	s_waitcnt lgkmcnt(1)
	v_mfma_f32_32x32x16_bf16 v[16:31], v[224:227], v[10:13], v[16:31]
	s_waitcnt lgkmcnt(0)
	v_mfma_f32_32x32x16_bf16 v[16:31], v[220:223], v[6:9], v[16:31]
	ds_read_b128 v[220:223], v217 offset:34912
	s_waitcnt lgkmcnt(0)
	v_mfma_f32_32x32x16_bf16 v[16:31], v[220:223], v[2:5], v[16:31]
	ds_read_b128 v[220:223], v217 offset:39424
	s_waitcnt lgkmcnt(0)
	v_mfma_f32_32x32x16_bf16 v[32:47], v[220:223], v[128:131], v[32:47]
	ds_read_b128 v[220:223], v217 offset:39456
	s_waitcnt lgkmcnt(0)
	v_mfma_f32_32x32x16_bf16 v[32:47], v[220:223], v[10:13], v[32:47]
	ds_read_b128 v[220:223], v217 offset:39488
	s_waitcnt lgkmcnt(0)
	v_mfma_f32_32x32x16_bf16 v[32:47], v[220:223], v[6:9], v[32:47]
	ds_read_b128 v[220:223], v217 offset:39520
	s_waitcnt lgkmcnt(0)
	v_mfma_f32_32x32x16_bf16 v[32:47], v[220:223], v[2:5], v[32:47]
	ds_read_b128 v[220:223], v217 offset:44032
	s_waitcnt lgkmcnt(0)
	v_mfma_f32_32x32x16_bf16 v[48:63], v[220:223], v[128:131], v[48:63]
	ds_read_b128 v[220:223], v217 offset:44064
	s_waitcnt lgkmcnt(0)
	v_mfma_f32_32x32x16_bf16 v[48:63], v[220:223], v[10:13], v[48:63]
	ds_read_b128 v[220:223], v217 offset:44096
	s_waitcnt lgkmcnt(0)
	v_mfma_f32_32x32x16_bf16 v[48:63], v[220:223], v[6:9], v[48:63]
	ds_read_b128 v[220:223], v217 offset:44128
	s_waitcnt lgkmcnt(0)
	v_mfma_f32_32x32x16_bf16 v[48:63], v[220:223], v[2:5], v[48:63]
	ds_read_b128 v[220:223], v217 offset:48640
	s_waitcnt lgkmcnt(0)
	v_mfma_f32_32x32x16_bf16 v[64:79], v[220:223], v[128:131], v[64:79]
	ds_read_b128 v[128:131], v217 offset:48672
	s_waitcnt lgkmcnt(0)
	v_mfma_f32_32x32x16_bf16 v[64:79], v[128:131], v[10:13], v[64:79]
	ds_read_b128 v[10:13], v217 offset:48704
	s_waitcnt lgkmcnt(0)
	v_mfma_f32_32x32x16_bf16 v[64:79], v[10:13], v[6:9], v[64:79]
	ds_read_b128 v[6:9], v217 offset:48736
	s_waitcnt lgkmcnt(0)
; DI u16 f2bf(float x) { return (u16)(pk2bf(x, 0.f) & 0xffffu); }
; DI int crow(int i, int h) { return (i & 3) + 8 * (i >> 2) + 4 * h; }
; DI void phase_scan_c(int wv_, int vb_, int nvb_, char* ws_, const Ctx& p, char* smem, int half) {
;     ...
;       u16* op = O + ((size_t)b * SEQ + (size_t)(half * 32 + nc) * 64) * 1024 + hd * 128 + dv0 + c;
; #pragma unroll
;       for (int tb = 0; tb < 2; ++tb)
; #pragma unroll
;         for (int i = 0; i < 16; ++i) op[(size_t)(tb * 32 + crow(i, h)) * 1024] = f2bf(Oa[tb][i]);
;       __syncthreads();
	v_mfma_f32_32x32x16_bf16 v[64:79], v[6:9], v[2:5], v[64:79]
	v_lshl_add_u64 v[2:3], v[184:185], 0, s[16:17]
	v_add_co_u32_e32 v4, vcc, s52, v2
	v_lshl_add_u64 v[184:185], v[184:185], 0, s[96:97]
	s_nop 0
	v_addc_co_u32_e32 v5, vcc, 0, v3, vcc
	v_add_co_u32_e32 v6, vcc, s62, v2
	s_nop 1
	v_addc_co_u32_e32 v7, vcc, 0, v3, vcc
	global_store_short v[6:7], v0, off offset:-4096
	v_cvt_pk_bf16_f32 v0, v97, s0
	global_store_short v[4:5], v0, off offset:2048
	v_cvt_pk_bf16_f32 v0, v98, s0
	v_add_co_u32_e32 v4, vcc, s63, v2
	global_store_short v[6:7], v0, off
	v_cvt_pk_bf16_f32 v0, v99, s0
	v_addc_co_u32_e32 v5, vcc, 0, v3, vcc
	global_store_short v[6:7], v0, off offset:2048
	v_add_co_u32_e32 v6, vcc, s64, v2
	v_cvt_pk_bf16_f32 v0, v100, s0
	s_nop 0
	v_addc_co_u32_e32 v7, vcc, 0, v3, vcc
	global_store_short v[6:7], v0, off offset:-4096
	v_cvt_pk_bf16_f32 v0, v101, s0
	global_store_short v[4:5], v0, off offset:2048
	v_cvt_pk_bf16_f32 v0, v102, s0
	v_add_co_u32_e32 v4, vcc, s65, v2
	global_store_short v[6:7], v0, off
	v_cvt_pk_bf16_f32 v0, v103, s0
	v_addc_co_u32_e32 v5, vcc, 0, v3, vcc
	global_store_short v[6:7], v0, off offset:2048
	v_add_co_u32_e32 v6, vcc, s68, v2
	v_cvt_pk_bf16_f32 v0, v104, s0
	s_nop 0
	v_addc_co_u32_e32 v7, vcc, 0, v3, vcc
	global_store_short v[6:7], v0, off offset:-4096
	v_cvt_pk_bf16_f32 v0, v105, s0
	global_store_short v[4:5], v0, off offset:2048
	v_cvt_pk_bf16_f32 v0, v106, s0
	v_add_co_u32_e32 v4, vcc, s69, v2
	global_store_short v[6:7], v0, off
	v_cvt_pk_bf16_f32 v0, v107, s0
	v_addc_co_u32_e32 v5, vcc, 0, v3, vcc
	global_store_short v[6:7], v0, off offset:2048
	v_add_co_u32_e32 v6, vcc, s72, v2
	v_cvt_pk_bf16_f32 v0, v108, s0
	s_nop 0
	v_addc_co_u32_e32 v7, vcc, 0, v3, vcc
	global_store_short v[6:7], v0, off offset:-4096
	v_cvt_pk_bf16_f32 v0, v109, s0
	global_store_short v[4:5], v0, off offset:2048
	v_cvt_pk_bf16_f32 v0, v110, s0
	v_add_co_u32_e32 v4, vcc, s73, v2
	global_store_short v[6:7], v0, off
	v_cvt_pk_bf16_f32 v0, v111, s0
	v_addc_co_u32_e32 v5, vcc, 0, v3, vcc
	global_store_short v[6:7], v0, off offset:2048
	v_add_co_u32_e32 v6, vcc, s76, v2
	v_cvt_pk_bf16_f32 v0, v80, s0
	s_nop 0
	v_addc_co_u32_e32 v7, vcc, 0, v3, vcc
	global_store_short v[6:7], v0, off offset:-4096
	v_cvt_pk_bf16_f32 v0, v81, s0
	global_store_short v[4:5], v0, off offset:2048
	v_cvt_pk_bf16_f32 v0, v82, s0
	v_add_co_u32_e32 v4, vcc, s77, v2
	global_store_short v[6:7], v0, off
	v_cvt_pk_bf16_f32 v0, v83, s0
	v_addc_co_u32_e32 v5, vcc, 0, v3, vcc
	global_store_short v[6:7], v0, off offset:2048
	v_add_co_u32_e32 v6, vcc, s88, v2
	v_cvt_pk_bf16_f32 v0, v84, s0
	s_nop 0
	v_addc_co_u32_e32 v7, vcc, 0, v3, vcc
	global_store_short v[6:7], v0, off offset:-4096
	v_cvt_pk_bf16_f32 v0, v85, s0
	global_store_short v[4:5], v0, off offset:2048
	v_cvt_pk_bf16_f32 v0, v86, s0
	v_add_co_u32_e32 v4, vcc, s89, v2
	global_store_short v[6:7], v0, off
	v_cvt_pk_bf16_f32 v0, v87, s0
	v_addc_co_u32_e32 v5, vcc, 0, v3, vcc
	global_store_short v[6:7], v0, off offset:2048
	v_add_co_u32_e32 v6, vcc, s90, v2
	v_cvt_pk_bf16_f32 v0, v88, s0
	s_nop 0
	v_addc_co_u32_e32 v7, vcc, 0, v3, vcc
	global_store_short v[6:7], v0, off offset:-4096
	v_cvt_pk_bf16_f32 v0, v89, s0
	global_store_short v[4:5], v0, off offset:2048
	v_add_co_u32_e32 v4, vcc, s91, v2
	v_cvt_pk_bf16_f32 v0, v90, s0
	s_nop 0
	v_addc_co_u32_e32 v5, vcc, 0, v3, vcc
	global_store_short v[6:7], v0, off
	v_cvt_pk_bf16_f32 v0, v91, s0
	v_add_co_u32_e32 v2, vcc, s94, v2
	global_store_short v[6:7], v0, off offset:2048
	v_cvt_pk_bf16_f32 v0, v92, s0
	v_addc_co_u32_e32 v3, vcc, 0, v3, vcc
	global_store_short v[2:3], v0, off offset:-4096
	v_cvt_pk_bf16_f32 v0, v93, s0
	global_store_short v[4:5], v0, off offset:2048
	v_cvt_pk_bf16_f32 v0, v94, s0
	v_cmp_eq_u32_e32 vcc, 0, v218
	global_store_short v[2:3], v0, off
	v_cvt_pk_bf16_f32 v0, v95, s0
	s_and_b64 vcc, exec, vcc
	global_store_short v[2:3], v0, off offset:2048
	s_barrier
; DI void phase_scan_c(int wv_, int vb_, int nvb_, char* ws_, const Ctx& p, char* smem, int half) {
;     ...
;       __syncthreads();
;       SWRITE()
;       __syncthreads();
;     }
;     ...
;     if (half == 0) {
; #pragma unroll
;       for (int mb = 0; mb < 4; ++mb)
; #pragma unroll
;         for (int i = 0; i < 16; ++i) stp[(mb * 16 + i) * 64] = S[mb][i];
;     }
	s_waitcnt vmcnt(43)
	ds_write_b128 v176, v[112:115]
	s_waitcnt vmcnt(42)
	ds_write_b128 v176, v[116:119] offset:17408
	s_waitcnt vmcnt(41)
	ds_write_b128 v177, v[120:123] offset:34816
	s_waitcnt vmcnt(40)
	ds_write_b128 v178, v[124:127]
	s_waitcnt vmcnt(39)
	ds_write_b128 v178, v[132:135] offset:17408
	s_waitcnt vmcnt(38)
	ds_write_b128 v179, v[136:139] offset:34816
	s_waitcnt vmcnt(37)
	ds_write_b128 v180, v[140:143]
	s_waitcnt vmcnt(36)
	ds_write_b128 v180, v[144:147] offset:17408
	s_waitcnt vmcnt(35)
	ds_write_b128 v181, v[148:151] offset:34816
	ds_write_b128 v182, v[152:155]
	s_waitcnt vmcnt(34)
	ds_write_b128 v182, v[156:159] offset:17408
	ds_write_b128 v183, v[160:163] offset:34816
	s_waitcnt vmcnt(33)
	ds_write_b128 v202, v[164:167] offset:53248
	s_waitcnt vmcnt(32)
	ds_write_b128 v203, v[168:171] offset:53248
	s_waitcnt lgkmcnt(0)
	s_barrier
	s_cbranch_vccz .LBB0_232
	s_waitcnt vmcnt(0)
	s_barrier
	s_setprio 0
	s_mov_b32 s52, 0x6600000
	s_andn2_b64 vcc, exec, s[60:61]
	s_cbranch_vccnz .LBB0_235
	s_movk_i32 s0, 0x1000
	v_add_co_u32_e32 v2, vcc, s0, v172
	s_movk_i32 s0, 0x2000
	s_nop 0
	v_addc_co_u32_e32 v3, vcc, 0, v173, vcc
	v_add_co_u32_e32 v4, vcc, s0, v172
	s_movk_i32 s0, 0x3000
	s_nop 0
	v_addc_co_u32_e32 v5, vcc, 0, v173, vcc
	global_store_dword v[172:173], v16, off
	global_store_dword v[172:173], v17, off offset:256
	global_store_dword v[172:173], v18, off offset:512
	global_store_dword v[172:173], v19, off offset:768
	global_store_dword v[172:173], v20, off offset:1024
	global_store_dword v[172:173], v21, off offset:1280
	global_store_dword v[172:173], v22, off offset:1536
	global_store_dword v[172:173], v23, off offset:1792
	global_store_dword v[172:173], v24, off offset:2048
	global_store_dword v[172:173], v25, off offset:2304
	global_store_dword v[172:173], v26, off offset:2560
	global_store_dword v[172:173], v27, off offset:2816
	global_store_dword v[172:173], v28, off offset:3072
	global_store_dword v[172:173], v29, off offset:3328
	global_store_dword v[172:173], v30, off offset:3584
	global_store_dword v[172:173], v31, off offset:3840
	global_store_dword v[4:5], v32, off offset:-4096
	global_store_dword v[2:3], v33, off offset:256
	global_store_dword v[2:3], v34, off offset:512
	global_store_dword v[2:3], v35, off offset:768
	global_store_dword v[2:3], v36, off offset:1024
	global_store_dword v[2:3], v37, off offset:1280
	global_store_dword v[2:3], v38, off offset:1536
	global_store_dword v[2:3], v39, off offset:1792
	global_store_dword v[2:3], v40, off offset:2048
	global_store_dword v[2:3], v41, off offset:2304
	global_store_dword v[2:3], v42, off offset:2560
	global_store_dword v[2:3], v43, off offset:2816
	global_store_dword v[2:3], v44, off offset:3072
	global_store_dword v[2:3], v45, off offset:3328
	global_store_dword v[2:3], v46, off offset:3584
	global_store_dword v[2:3], v47, off offset:3840
	global_store_dword v[4:5], v48, off
	global_store_dword v[4:5], v49, off offset:256
	global_store_dword v[4:5], v50, off offset:512
	global_store_dword v[4:5], v51, off offset:768
	global_store_dword v[4:5], v52, off offset:1024
	global_store_dword v[4:5], v53, off offset:1280
	global_store_dword v[4:5], v54, off offset:1536
	global_store_dword v[4:5], v55, off offset:1792
	global_store_dword v[4:5], v56, off offset:2048
	global_store_dword v[4:5], v57, off offset:2304
	global_store_dword v[4:5], v58, off offset:2560
	global_store_dword v[4:5], v59, off offset:2816
	global_store_dword v[4:5], v60, off offset:3072
	global_store_dword v[4:5], v61, off offset:3328
	global_store_dword v[4:5], v62, off offset:3584
	global_store_dword v[4:5], v63, off offset:3840
	v_add_co_u32_e32 v2, vcc, s0, v172
	s_nop 1
	v_addc_co_u32_e32 v3, vcc, 0, v173, vcc
	global_store_dword v[2:3], v64, off
	global_store_dword v[2:3], v65, off offset:256
	global_store_dword v[2:3], v66, off offset:512
	global_store_dword v[2:3], v67, off offset:768
	global_store_dword v[2:3], v68, off offset:1024
	global_store_dword v[2:3], v69, off offset:1280
	global_store_dword v[2:3], v70, off offset:1536
	global_store_dword v[2:3], v71, off offset:1792
	global_store_dword v[2:3], v72, off offset:2048
	global_store_dword v[2:3], v73, off offset:2304
	global_store_dword v[2:3], v74, off offset:2560
	global_store_dword v[2:3], v75, off offset:2816
	global_store_dword v[2:3], v76, off offset:3072
	global_store_dword v[2:3], v77, off offset:3328
	global_store_dword v[2:3], v78, off offset:3584
	global_store_dword v[2:3], v79, off offset:3840
	s_branch .LBB0_235
